# sample_out_block K loop: coalesced row loads staged through wave-private LDS instead of per-lane fragment loads
# speedup vs baseline: 1.0394x; 1.0187x over previous
; #define MFMA16(a, b, c) __builtin_amdgcn_mfma_f32_16x16x32_bf16((a), (b), (c), 0, 0, 0)
; __device__ __forceinline__ void sample_out_block(LAS unsigned char* lds, const bf16_t* A, const bf16_t* Bt, int K, bf16_t* xb, float* sspart, int blk, int tid) {
;     ...
;     {
;         const bf16_t* ap = A + (size_t)(r0 + l15) * K + wave * kq + 8 * g;
;         const bf16_t* bp = Bt + (size_t)(64 * cg + l15) * K + wave * kq + 8 * g;
;         bf16x8 af[2][2], bf[2][4], afn[2][2], bfn[2][4];
; #pragma unroll
;         for (int s = 0; s < 2; ++s) {
; #pragma unroll
;             for (int ra = 0; ra < 2; ++ra) af[s][ra] = *(const bf16x8*)(ap + (size_t)(16 * ra) * K + 32 * s);
; #pragma unroll
;             for (int nt = 0; nt < 4; ++nt) bf[s][nt] = *(const bf16x8*)(bp + (size_t)(16 * nt) * K + 32 * s);
;         }
;         for (int k0 = 0; k0 < kq; k0 += 64) {
;             const int k1 = (k0 + 64 < kq) ? k0 + 64 : k0;
; #pragma unroll
;             for (int s = 0; s < 2; ++s) {
; #pragma unroll
;                 for (int ra = 0; ra < 2; ++ra) afn[s][ra] = *(const bf16x8*)(ap + (size_t)(16 * ra) * K + k1 + 32 * s);
; #pragma unroll
;                 for (int nt = 0; nt < 4; ++nt) bfn[s][nt] = *(const bf16x8*)(bp + (size_t)(16 * nt) * K + k1 + 32 * s);
;             }
; #pragma unroll
;             for (int s = 0; s < 2; ++s)
; #pragma unroll
;                 for (int ra = 0; ra < 2; ++ra)
; #pragma unroll
;                     for (int nt = 0; nt < 4; ++nt) acc[ra][nt] = MFMA16(af[s][ra], bf[s][nt], acc[ra][nt]);
.LBB0_542:
	s_and_b32 s27, s34, 0xffffffe0
	s_addk_i32 s27, 0x2000
	s_and_b32 s26, s34, 31
	v_or_b32_e32 v8, s27, v30
	v_ashrrev_i32_e32 v9, 31, v8
	s_lshl_b32 s35, s26, 6
	v_lshlrev_b64 v[8:9], 13, v[8:9]
	v_or_b32_e32 v0, s35, v30
	v_lshl_add_u64 v[10:11], v[2:3], 0, v[8:9]
	v_lshlrev_b32_e32 v0, 13, v0
	v_lshl_add_u64 v[16:17], v[4:5], 0, v[0:1]
	v_add_co_u32_e32 v8, vcc, 0x20000, v10
	s_mov_b64 s[10:11], vcc
	v_add_co_u32_e32 v12, vcc, 0x20000, v16
	v_readfirstlane_b32 s36, v139
	s_lshr_b32 s36, s36, 6
	s_and_b32 s37, s34, 0xffffffe0
	s_addk_i32 s37, 0x2000
	s_and_b32 s38, s34, 31
	s_lshl_b32 s38, s38, 6
	s_lshl_b32 s39, s37, 13
	s_mul_i32 s40, s36, 0x400
	s_add_u32 s42, s24, s39
	s_addc_u32 s43, s25, 0
	s_add_u32 s42, s42, s40
	s_addc_u32 s43, s43, 0
	s_lshl_b32 s41, s30, 1
	s_lshl_b32 s39, s38, 13
	s_add_u32 s44, s28, s41
	s_addc_u32 s45, s29, 0
	s_add_u32 s44, s44, s39
	s_addc_u32 s45, s45, 0
	s_add_u32 s44, s44, s40
	s_addc_u32 s45, s45, 0
	v_lshrrev_b32_e32 v227, 3, v215
	v_and_b32_e32 v228, 7, v215
	v_lshlrev_b32_e32 v198, 13, v227
	v_lshl_add_u32 v198, v228, 4, v198
	v_add_u32_e32 v199, 0x10000, v198
	v_add_u32_e32 v200, 0x20000, v198
	v_add_u32_e32 v201, 0x30000, v198
	v_add_u32_e32 v202, 0x40000, v198
	v_add_u32_e32 v203, 0x50000, v198
	v_add_u32_e32 v204, 0x60000, v198
	v_add_u32_e32 v205, 0x70000, v198
	s_lshl_b32 s46, s36, 13
	s_mul_i32 s47, s36, 0x1800
	s_add_i32 s47, s47, 0x10000
	v_mul_u32_u24_e32 v206, 0x90, v227
	v_lshl_add_u32 v206, v228, 4, v206
	v_add_u32_e32 v207, s47, v206
	v_add_u32_e32 v206, s46, v206
	v_and_b32_e32 v227, 15, v215
	v_lshrrev_b32_e32 v228, 4, v215
	v_mul_u32_u24_e32 v208, 0x90, v227
	v_lshl_add_u32 v208, v228, 4, v208
	v_add_u32_e32 v209, s47, v208
	v_add_u32_e32 v208, s46, v208
	v_add_u32_e32 v226, 0x1b00, v208
	v_subrev_u32_e32 v228, 0x480, v209
	v_cmp_gt_u32_e32 vcc, 8, v227
	v_cndmask_b32_e32 v226, v228, v226, vcc
	global_load_dwordx4 v[34:37], v198, s[42:43]
	global_load_dwordx4 v[38:41], v199, s[42:43]
	global_load_dwordx4 v[42:45], v200, s[42:43]
	global_load_dwordx4 v[46:49], v201, s[42:43]
	global_load_dwordx4 v[50:53], v198, s[44:45]
	global_load_dwordx4 v[54:57], v199, s[44:45]
	global_load_dwordx4 v[58:61], v200, s[44:45]
	global_load_dwordx4 v[62:65], v201, s[44:45]
	global_load_dwordx4 v[66:69], v202, s[44:45]
	global_load_dwordx4 v[70:73], v203, s[44:45]
	global_load_dwordx4 v[74:77], v204, s[44:45]
	global_load_dwordx4 v[78:81], v205, s[44:45]
	global_load_dwordx4 v[82:85], v198, s[42:43] offset:128
	global_load_dwordx4 v[86:89], v199, s[42:43] offset:128
	global_load_dwordx4 v[90:93], v200, s[42:43] offset:128
	global_load_dwordx4 v[94:97], v201, s[42:43] offset:128
	global_load_dwordx4 v[98:101], v198, s[44:45] offset:128
	global_load_dwordx4 v[102:105], v199, s[44:45] offset:128
	global_load_dwordx4 v[106:109], v200, s[44:45] offset:128
	global_load_dwordx4 v[110:113], v201, s[44:45] offset:128
	global_load_dwordx4 v[114:117], v202, s[44:45] offset:128
	global_load_dwordx4 v[118:121], v203, s[44:45] offset:128
	global_load_dwordx4 v[122:125], v204, s[44:45] offset:128
	global_load_dwordx4 v[126:129], v205, s[44:45] offset:128
	s_waitcnt vmcnt(12)
	ds_write_b128 v206, v[34:37]
	ds_write_b128 v206, v[38:41] offset:1152
	ds_write_b128 v206, v[42:45] offset:2304
	ds_write_b128 v206, v[46:49] offset:3456
	ds_write_b128 v206, v[50:53] offset:4608
	ds_write_b128 v206, v[54:57] offset:5760
	ds_write_b128 v206, v[58:61] offset:6912
	ds_write_b128 v207, v[62:65]
	ds_write_b128 v207, v[66:69] offset:1152
	ds_write_b128 v207, v[70:73] offset:2304
	ds_write_b128 v207, v[74:77] offset:3456
	ds_write_b128 v207, v[78:81] offset:4608
	global_load_dwordx4 v[34:37], v198, s[42:43] offset:256
	global_load_dwordx4 v[38:41], v199, s[42:43] offset:256
	global_load_dwordx4 v[42:45], v200, s[42:43] offset:256
	global_load_dwordx4 v[46:49], v201, s[42:43] offset:256
	global_load_dwordx4 v[50:53], v198, s[44:45] offset:256
	global_load_dwordx4 v[54:57], v199, s[44:45] offset:256
	global_load_dwordx4 v[58:61], v200, s[44:45] offset:256
	global_load_dwordx4 v[62:65], v201, s[44:45] offset:256
	global_load_dwordx4 v[66:69], v202, s[44:45] offset:256
	global_load_dwordx4 v[70:73], v203, s[44:45] offset:256
	global_load_dwordx4 v[74:77], v204, s[44:45] offset:256
	global_load_dwordx4 v[78:81], v205, s[44:45] offset:256
	ds_read_b128 v[146:149], v208 offset:0
	ds_read_b128 v[150:153], v208 offset:2304
	ds_read_b128 v[154:157], v208 offset:4608
	ds_read_b128 v[158:161], v226
	ds_read_b128 v[162:165], v209 offset:1152
	ds_read_b128 v[166:169], v209 offset:3456
	ds_read_b128 v[170:173], v208 offset:64
	ds_read_b128 v[174:177], v208 offset:2368
	ds_read_b128 v[178:181], v208 offset:4672
	ds_read_b128 v[182:185], v226 offset:64
	ds_read_b128 v[186:189], v209 offset:1216
	ds_read_b128 v[190:193], v209 offset:3520
	s_waitcnt lgkmcnt(6)
	v_mfma_f32_16x16x32_bf16 v[8:11], v[146:149], v[154:157], 0
	v_mfma_f32_16x16x32_bf16 v[12:15], v[146:149], v[158:161], 0
	v_mfma_f32_16x16x32_bf16 v[16:19], v[146:149], v[162:165], 0
	v_mfma_f32_16x16x32_bf16 v[20:23], v[146:149], v[166:169], 0
	v_mfma_f32_16x16x32_bf16 v[24:27], v[150:153], v[154:157], 0
	v_mfma_f32_16x16x32_bf16 v[130:133], v[150:153], v[158:161], 0
	v_mfma_f32_16x16x32_bf16 v[134:137], v[150:153], v[162:165], 0
	v_mfma_f32_16x16x32_bf16 v[194:197], v[150:153], v[166:169], 0
	s_waitcnt lgkmcnt(0)
; #define MFMA16(a, b, c) __builtin_amdgcn_mfma_f32_16x16x32_bf16((a), (b), (c), 0, 0, 0)
; __device__ __forceinline__ void sample_out_block(LAS unsigned char* lds, const bf16_t* A, const bf16_t* Bt, int K, bf16_t* xb, float* sspart, int blk, int tid) {
;     ...
;         for (int k0 = 0; k0 < kq; k0 += 64) {
;             const int k1 = (k0 + 64 < kq) ? k0 + 64 : k0;
; #pragma unroll
;             for (int s = 0; s < 2; ++s) {
; #pragma unroll
;                 for (int ra = 0; ra < 2; ++ra) afn[s][ra] = *(const bf16x8*)(ap + (size_t)(16 * ra) * K + k1 + 32 * s);
; #pragma unroll
;                 for (int nt = 0; nt < 4; ++nt) bfn[s][nt] = *(const bf16x8*)(bp + (size_t)(16 * nt) * K + k1 + 32 * s);
;             }
; #pragma unroll
;             for (int s = 0; s < 2; ++s)
; #pragma unroll
;                 for (int ra = 0; ra < 2; ++ra)
; #pragma unroll
;                     for (int nt = 0; nt < 4; ++nt) acc[ra][nt] = MFMA16(af[s][ra], bf[s][nt], acc[ra][nt]);
	v_mfma_f32_16x16x32_bf16 v[8:11], v[170:173], v[178:181], v[8:11]
	v_mfma_f32_16x16x32_bf16 v[12:15], v[170:173], v[182:185], v[12:15]
	v_mfma_f32_16x16x32_bf16 v[16:19], v[170:173], v[186:189], v[16:19]
	v_mfma_f32_16x16x32_bf16 v[20:23], v[170:173], v[190:193], v[20:23]
	v_mfma_f32_16x16x32_bf16 v[24:27], v[174:177], v[178:181], v[24:27]
	v_mfma_f32_16x16x32_bf16 v[130:133], v[174:177], v[182:185], v[130:133]
	v_mfma_f32_16x16x32_bf16 v[134:137], v[174:177], v[186:189], v[134:137]
	v_mfma_f32_16x16x32_bf16 v[194:197], v[174:177], v[190:193], v[194:197]
	s_waitcnt vmcnt(12)
	ds_write_b128 v206, v[82:85]
	ds_write_b128 v206, v[86:89] offset:1152
	ds_write_b128 v206, v[90:93] offset:2304
	ds_write_b128 v206, v[94:97] offset:3456
	ds_write_b128 v206, v[98:101] offset:4608
	ds_write_b128 v206, v[102:105] offset:5760
	ds_write_b128 v206, v[106:109] offset:6912
	ds_write_b128 v207, v[110:113]
	ds_write_b128 v207, v[114:117] offset:1152
	ds_write_b128 v207, v[118:121] offset:2304
	ds_write_b128 v207, v[122:125] offset:3456
	ds_write_b128 v207, v[126:129] offset:4608
	global_load_dwordx4 v[82:85], v198, s[42:43] offset:384
	global_load_dwordx4 v[86:89], v199, s[42:43] offset:384
	global_load_dwordx4 v[90:93], v200, s[42:43] offset:384
	global_load_dwordx4 v[94:97], v201, s[42:43] offset:384
	global_load_dwordx4 v[98:101], v198, s[44:45] offset:384
	global_load_dwordx4 v[102:105], v199, s[44:45] offset:384
	global_load_dwordx4 v[106:109], v200, s[44:45] offset:384
	global_load_dwordx4 v[110:113], v201, s[44:45] offset:384
	global_load_dwordx4 v[114:117], v202, s[44:45] offset:384
	global_load_dwordx4 v[118:121], v203, s[44:45] offset:384
	global_load_dwordx4 v[122:125], v204, s[44:45] offset:384
	global_load_dwordx4 v[126:129], v205, s[44:45] offset:384
	ds_read_b128 v[146:149], v208 offset:0
	ds_read_b128 v[150:153], v208 offset:2304
	ds_read_b128 v[154:157], v208 offset:4608
	ds_read_b128 v[158:161], v226
	ds_read_b128 v[162:165], v209 offset:1152
	ds_read_b128 v[166:169], v209 offset:3456
	ds_read_b128 v[170:173], v208 offset:64
	ds_read_b128 v[174:177], v208 offset:2368
	ds_read_b128 v[178:181], v208 offset:4672
	ds_read_b128 v[182:185], v226 offset:64
	ds_read_b128 v[186:189], v209 offset:1216
	ds_read_b128 v[190:193], v209 offset:3520
	s_waitcnt lgkmcnt(6)
	v_mfma_f32_16x16x32_bf16 v[8:11], v[146:149], v[154:157], v[8:11]
	v_mfma_f32_16x16x32_bf16 v[12:15], v[146:149], v[158:161], v[12:15]
	v_mfma_f32_16x16x32_bf16 v[16:19], v[146:149], v[162:165], v[16:19]
	v_mfma_f32_16x16x32_bf16 v[20:23], v[146:149], v[166:169], v[20:23]
	v_mfma_f32_16x16x32_bf16 v[24:27], v[150:153], v[154:157], v[24:27]
	v_mfma_f32_16x16x32_bf16 v[130:133], v[150:153], v[158:161], v[130:133]
	v_mfma_f32_16x16x32_bf16 v[134:137], v[150:153], v[162:165], v[134:137]
	v_mfma_f32_16x16x32_bf16 v[194:197], v[150:153], v[166:169], v[194:197]
	s_waitcnt lgkmcnt(0)
	v_mfma_f32_16x16x32_bf16 v[8:11], v[170:173], v[178:181], v[8:11]
	v_mfma_f32_16x16x32_bf16 v[12:15], v[170:173], v[182:185], v[12:15]
	v_mfma_f32_16x16x32_bf16 v[16:19], v[170:173], v[186:189], v[16:19]
	v_mfma_f32_16x16x32_bf16 v[20:23], v[170:173], v[190:193], v[20:23]
	v_mfma_f32_16x16x32_bf16 v[24:27], v[174:177], v[178:181], v[24:27]
	v_mfma_f32_16x16x32_bf16 v[130:133], v[174:177], v[182:185], v[130:133]
	v_mfma_f32_16x16x32_bf16 v[134:137], v[174:177], v[186:189], v[134:137]
	v_mfma_f32_16x16x32_bf16 v[194:197], v[174:177], v[190:193], v[194:197]
	s_waitcnt vmcnt(12)
	ds_write_b128 v206, v[34:37]
	ds_write_b128 v206, v[38:41] offset:1152
	ds_write_b128 v206, v[42:45] offset:2304
	ds_write_b128 v206, v[46:49] offset:3456
	ds_write_b128 v206, v[50:53] offset:4608
	ds_write_b128 v206, v[54:57] offset:5760
	ds_write_b128 v206, v[58:61] offset:6912
	ds_write_b128 v207, v[62:65]
	ds_write_b128 v207, v[66:69] offset:1152
	ds_write_b128 v207, v[70:73] offset:2304
	ds_write_b128 v207, v[74:77] offset:3456
	ds_write_b128 v207, v[78:81] offset:4608
	global_load_dwordx4 v[34:37], v198, s[42:43] offset:512
	global_load_dwordx4 v[38:41], v199, s[42:43] offset:512
	global_load_dwordx4 v[42:45], v200, s[42:43] offset:512
	global_load_dwordx4 v[46:49], v201, s[42:43] offset:512
	global_load_dwordx4 v[50:53], v198, s[44:45] offset:512
	global_load_dwordx4 v[54:57], v199, s[44:45] offset:512
	global_load_dwordx4 v[58:61], v200, s[44:45] offset:512
	global_load_dwordx4 v[62:65], v201, s[44:45] offset:512
	global_load_dwordx4 v[66:69], v202, s[44:45] offset:512
	global_load_dwordx4 v[70:73], v203, s[44:45] offset:512
	global_load_dwordx4 v[74:77], v204, s[44:45] offset:512
	global_load_dwordx4 v[78:81], v205, s[44:45] offset:512
	ds_read_b128 v[146:149], v208 offset:0
	ds_read_b128 v[150:153], v208 offset:2304
	ds_read_b128 v[154:157], v208 offset:4608
	ds_read_b128 v[158:161], v226
	ds_read_b128 v[162:165], v209 offset:1152
	ds_read_b128 v[166:169], v209 offset:3456
	ds_read_b128 v[170:173], v208 offset:64
	ds_read_b128 v[174:177], v208 offset:2368
	ds_read_b128 v[178:181], v208 offset:4672
	ds_read_b128 v[182:185], v226 offset:64
	ds_read_b128 v[186:189], v209 offset:1216
	ds_read_b128 v[190:193], v209 offset:3520
	s_waitcnt lgkmcnt(6)
	v_mfma_f32_16x16x32_bf16 v[8:11], v[146:149], v[154:157], v[8:11]
	v_mfma_f32_16x16x32_bf16 v[12:15], v[146:149], v[158:161], v[12:15]
	v_mfma_f32_16x16x32_bf16 v[16:19], v[146:149], v[162:165], v[16:19]
	v_mfma_f32_16x16x32_bf16 v[20:23], v[146:149], v[166:169], v[20:23]
	v_mfma_f32_16x16x32_bf16 v[24:27], v[150:153], v[154:157], v[24:27]
	v_mfma_f32_16x16x32_bf16 v[130:133], v[150:153], v[158:161], v[130:133]
	v_mfma_f32_16x16x32_bf16 v[134:137], v[150:153], v[162:165], v[134:137]
	v_mfma_f32_16x16x32_bf16 v[194:197], v[150:153], v[166:169], v[194:197]
	s_waitcnt lgkmcnt(0)
; #define MFMA16(a, b, c) __builtin_amdgcn_mfma_f32_16x16x32_bf16((a), (b), (c), 0, 0, 0)
; __device__ __forceinline__ void sample_out_block(LAS unsigned char* lds, const bf16_t* A, const bf16_t* Bt, int K, bf16_t* xb, float* sspart, int blk, int tid) {
;     ...
;         for (int k0 = 0; k0 < kq; k0 += 64) {
;             const int k1 = (k0 + 64 < kq) ? k0 + 64 : k0;
; #pragma unroll
;             for (int s = 0; s < 2; ++s) {
; #pragma unroll
;                 for (int ra = 0; ra < 2; ++ra) afn[s][ra] = *(const bf16x8*)(ap + (size_t)(16 * ra) * K + k1 + 32 * s);
; #pragma unroll
;                 for (int nt = 0; nt < 4; ++nt) bfn[s][nt] = *(const bf16x8*)(bp + (size_t)(16 * nt) * K + k1 + 32 * s);
;             }
; #pragma unroll
;             for (int s = 0; s < 2; ++s)
; #pragma unroll
;                 for (int ra = 0; ra < 2; ++ra)
; #pragma unroll
;                     for (int nt = 0; nt < 4; ++nt) acc[ra][nt] = MFMA16(af[s][ra], bf[s][nt], acc[ra][nt]);
	v_mfma_f32_16x16x32_bf16 v[8:11], v[170:173], v[178:181], v[8:11]
	v_mfma_f32_16x16x32_bf16 v[12:15], v[170:173], v[182:185], v[12:15]
	v_mfma_f32_16x16x32_bf16 v[16:19], v[170:173], v[186:189], v[16:19]
	v_mfma_f32_16x16x32_bf16 v[20:23], v[170:173], v[190:193], v[20:23]
	v_mfma_f32_16x16x32_bf16 v[24:27], v[174:177], v[178:181], v[24:27]
	v_mfma_f32_16x16x32_bf16 v[130:133], v[174:177], v[182:185], v[130:133]
	v_mfma_f32_16x16x32_bf16 v[134:137], v[174:177], v[186:189], v[134:137]
	v_mfma_f32_16x16x32_bf16 v[194:197], v[174:177], v[190:193], v[194:197]
	s_waitcnt vmcnt(12)
	ds_write_b128 v206, v[82:85]
	ds_write_b128 v206, v[86:89] offset:1152
	ds_write_b128 v206, v[90:93] offset:2304
	ds_write_b128 v206, v[94:97] offset:3456
	ds_write_b128 v206, v[98:101] offset:4608
	ds_write_b128 v206, v[102:105] offset:5760
	ds_write_b128 v206, v[106:109] offset:6912
	ds_write_b128 v207, v[110:113]
	ds_write_b128 v207, v[114:117] offset:1152
	ds_write_b128 v207, v[118:121] offset:2304
	ds_write_b128 v207, v[122:125] offset:3456
	ds_write_b128 v207, v[126:129] offset:4608
	global_load_dwordx4 v[82:85], v198, s[42:43] offset:640
	global_load_dwordx4 v[86:89], v199, s[42:43] offset:640
	global_load_dwordx4 v[90:93], v200, s[42:43] offset:640
	global_load_dwordx4 v[94:97], v201, s[42:43] offset:640
	global_load_dwordx4 v[98:101], v198, s[44:45] offset:640
	global_load_dwordx4 v[102:105], v199, s[44:45] offset:640
	global_load_dwordx4 v[106:109], v200, s[44:45] offset:640
	global_load_dwordx4 v[110:113], v201, s[44:45] offset:640
	global_load_dwordx4 v[114:117], v202, s[44:45] offset:640
	global_load_dwordx4 v[118:121], v203, s[44:45] offset:640
	global_load_dwordx4 v[122:125], v204, s[44:45] offset:640
	global_load_dwordx4 v[126:129], v205, s[44:45] offset:640
	ds_read_b128 v[146:149], v208 offset:0
	ds_read_b128 v[150:153], v208 offset:2304
	ds_read_b128 v[154:157], v208 offset:4608
	ds_read_b128 v[158:161], v226
	ds_read_b128 v[162:165], v209 offset:1152
	ds_read_b128 v[166:169], v209 offset:3456
	ds_read_b128 v[170:173], v208 offset:64
	ds_read_b128 v[174:177], v208 offset:2368
	ds_read_b128 v[178:181], v208 offset:4672
	ds_read_b128 v[182:185], v226 offset:64
	ds_read_b128 v[186:189], v209 offset:1216
	ds_read_b128 v[190:193], v209 offset:3520
	s_waitcnt lgkmcnt(6)
	v_mfma_f32_16x16x32_bf16 v[8:11], v[146:149], v[154:157], v[8:11]
	v_mfma_f32_16x16x32_bf16 v[12:15], v[146:149], v[158:161], v[12:15]
	v_mfma_f32_16x16x32_bf16 v[16:19], v[146:149], v[162:165], v[16:19]
	v_mfma_f32_16x16x32_bf16 v[20:23], v[146:149], v[166:169], v[20:23]
	v_mfma_f32_16x16x32_bf16 v[24:27], v[150:153], v[154:157], v[24:27]
	v_mfma_f32_16x16x32_bf16 v[130:133], v[150:153], v[158:161], v[130:133]
	v_mfma_f32_16x16x32_bf16 v[134:137], v[150:153], v[162:165], v[134:137]
	v_mfma_f32_16x16x32_bf16 v[194:197], v[150:153], v[166:169], v[194:197]
	s_waitcnt lgkmcnt(0)
	v_mfma_f32_16x16x32_bf16 v[8:11], v[170:173], v[178:181], v[8:11]
	v_mfma_f32_16x16x32_bf16 v[12:15], v[170:173], v[182:185], v[12:15]
	v_mfma_f32_16x16x32_bf16 v[16:19], v[170:173], v[186:189], v[16:19]
	v_mfma_f32_16x16x32_bf16 v[20:23], v[170:173], v[190:193], v[20:23]
	v_mfma_f32_16x16x32_bf16 v[24:27], v[174:177], v[178:181], v[24:27]
	v_mfma_f32_16x16x32_bf16 v[130:133], v[174:177], v[182:185], v[130:133]
	v_mfma_f32_16x16x32_bf16 v[134:137], v[174:177], v[186:189], v[134:137]
	v_mfma_f32_16x16x32_bf16 v[194:197], v[174:177], v[190:193], v[194:197]
	s_waitcnt vmcnt(12)
	ds_write_b128 v206, v[34:37]
	ds_write_b128 v206, v[38:41] offset:1152
	ds_write_b128 v206, v[42:45] offset:2304
	ds_write_b128 v206, v[46:49] offset:3456
	ds_write_b128 v206, v[50:53] offset:4608
	ds_write_b128 v206, v[54:57] offset:5760
	ds_write_b128 v206, v[58:61] offset:6912
	ds_write_b128 v207, v[62:65]
	ds_write_b128 v207, v[66:69] offset:1152
	ds_write_b128 v207, v[70:73] offset:2304
	ds_write_b128 v207, v[74:77] offset:3456
	ds_write_b128 v207, v[78:81] offset:4608
	global_load_dwordx4 v[34:37], v198, s[42:43] offset:768
	global_load_dwordx4 v[38:41], v199, s[42:43] offset:768
	global_load_dwordx4 v[42:45], v200, s[42:43] offset:768
	global_load_dwordx4 v[46:49], v201, s[42:43] offset:768
	global_load_dwordx4 v[50:53], v198, s[44:45] offset:768
	global_load_dwordx4 v[54:57], v199, s[44:45] offset:768
	global_load_dwordx4 v[58:61], v200, s[44:45] offset:768
	global_load_dwordx4 v[62:65], v201, s[44:45] offset:768
	global_load_dwordx4 v[66:69], v202, s[44:45] offset:768
	global_load_dwordx4 v[70:73], v203, s[44:45] offset:768
	global_load_dwordx4 v[74:77], v204, s[44:45] offset:768
	global_load_dwordx4 v[78:81], v205, s[44:45] offset:768
	ds_read_b128 v[146:149], v208 offset:0
	ds_read_b128 v[150:153], v208 offset:2304
	ds_read_b128 v[154:157], v208 offset:4608
	ds_read_b128 v[158:161], v226
	ds_read_b128 v[162:165], v209 offset:1152
	ds_read_b128 v[166:169], v209 offset:3456
	ds_read_b128 v[170:173], v208 offset:64
	ds_read_b128 v[174:177], v208 offset:2368
	ds_read_b128 v[178:181], v208 offset:4672
	ds_read_b128 v[182:185], v226 offset:64
	ds_read_b128 v[186:189], v209 offset:1216
	ds_read_b128 v[190:193], v209 offset:3520
	s_waitcnt lgkmcnt(6)
	v_mfma_f32_16x16x32_bf16 v[8:11], v[146:149], v[154:157], v[8:11]
	v_mfma_f32_16x16x32_bf16 v[12:15], v[146:149], v[158:161], v[12:15]
	v_mfma_f32_16x16x32_bf16 v[16:19], v[146:149], v[162:165], v[16:19]
	v_mfma_f32_16x16x32_bf16 v[20:23], v[146:149], v[166:169], v[20:23]
	v_mfma_f32_16x16x32_bf16 v[24:27], v[150:153], v[154:157], v[24:27]
	v_mfma_f32_16x16x32_bf16 v[130:133], v[150:153], v[158:161], v[130:133]
	v_mfma_f32_16x16x32_bf16 v[134:137], v[150:153], v[162:165], v[134:137]
	v_mfma_f32_16x16x32_bf16 v[194:197], v[150:153], v[166:169], v[194:197]
	s_waitcnt lgkmcnt(0)
; #define MFMA16(a, b, c) __builtin_amdgcn_mfma_f32_16x16x32_bf16((a), (b), (c), 0, 0, 0)
; __device__ __forceinline__ void sample_out_block(LAS unsigned char* lds, const bf16_t* A, const bf16_t* Bt, int K, bf16_t* xb, float* sspart, int blk, int tid) {
;     ...
;         for (int k0 = 0; k0 < kq; k0 += 64) {
;             const int k1 = (k0 + 64 < kq) ? k0 + 64 : k0;
; #pragma unroll
;             for (int s = 0; s < 2; ++s) {
; #pragma unroll
;                 for (int ra = 0; ra < 2; ++ra) afn[s][ra] = *(const bf16x8*)(ap + (size_t)(16 * ra) * K + k1 + 32 * s);
; #pragma unroll
;                 for (int nt = 0; nt < 4; ++nt) bfn[s][nt] = *(const bf16x8*)(bp + (size_t)(16 * nt) * K + k1 + 32 * s);
;             }
; #pragma unroll
;             for (int s = 0; s < 2; ++s)
; #pragma unroll
;                 for (int ra = 0; ra < 2; ++ra)
; #pragma unroll
;                     for (int nt = 0; nt < 4; ++nt) acc[ra][nt] = MFMA16(af[s][ra], bf[s][nt], acc[ra][nt]);
	v_mfma_f32_16x16x32_bf16 v[8:11], v[170:173], v[178:181], v[8:11]
	v_mfma_f32_16x16x32_bf16 v[12:15], v[170:173], v[182:185], v[12:15]
	v_mfma_f32_16x16x32_bf16 v[16:19], v[170:173], v[186:189], v[16:19]
	v_mfma_f32_16x16x32_bf16 v[20:23], v[170:173], v[190:193], v[20:23]
	v_mfma_f32_16x16x32_bf16 v[24:27], v[174:177], v[178:181], v[24:27]
	v_mfma_f32_16x16x32_bf16 v[130:133], v[174:177], v[182:185], v[130:133]
	v_mfma_f32_16x16x32_bf16 v[134:137], v[174:177], v[186:189], v[134:137]
	v_mfma_f32_16x16x32_bf16 v[194:197], v[174:177], v[190:193], v[194:197]
	s_waitcnt vmcnt(12)
	ds_write_b128 v206, v[82:85]
	ds_write_b128 v206, v[86:89] offset:1152
	ds_write_b128 v206, v[90:93] offset:2304
	ds_write_b128 v206, v[94:97] offset:3456
	ds_write_b128 v206, v[98:101] offset:4608
	ds_write_b128 v206, v[102:105] offset:5760
	ds_write_b128 v206, v[106:109] offset:6912
	ds_write_b128 v207, v[110:113]
	ds_write_b128 v207, v[114:117] offset:1152
	ds_write_b128 v207, v[118:121] offset:2304
	ds_write_b128 v207, v[122:125] offset:3456
	ds_write_b128 v207, v[126:129] offset:4608
	global_load_dwordx4 v[82:85], v198, s[42:43] offset:896
	global_load_dwordx4 v[86:89], v199, s[42:43] offset:896
	global_load_dwordx4 v[90:93], v200, s[42:43] offset:896
	global_load_dwordx4 v[94:97], v201, s[42:43] offset:896
	global_load_dwordx4 v[98:101], v198, s[44:45] offset:896
	global_load_dwordx4 v[102:105], v199, s[44:45] offset:896
	global_load_dwordx4 v[106:109], v200, s[44:45] offset:896
	global_load_dwordx4 v[110:113], v201, s[44:45] offset:896
	global_load_dwordx4 v[114:117], v202, s[44:45] offset:896
	global_load_dwordx4 v[118:121], v203, s[44:45] offset:896
	global_load_dwordx4 v[122:125], v204, s[44:45] offset:896
	global_load_dwordx4 v[126:129], v205, s[44:45] offset:896
	ds_read_b128 v[146:149], v208 offset:0
	ds_read_b128 v[150:153], v208 offset:2304
	ds_read_b128 v[154:157], v208 offset:4608
	ds_read_b128 v[158:161], v226
	ds_read_b128 v[162:165], v209 offset:1152
	ds_read_b128 v[166:169], v209 offset:3456
	ds_read_b128 v[170:173], v208 offset:64
	ds_read_b128 v[174:177], v208 offset:2368
	ds_read_b128 v[178:181], v208 offset:4672
	ds_read_b128 v[182:185], v226 offset:64
	ds_read_b128 v[186:189], v209 offset:1216
	ds_read_b128 v[190:193], v209 offset:3520
	s_waitcnt lgkmcnt(6)
	v_mfma_f32_16x16x32_bf16 v[8:11], v[146:149], v[154:157], v[8:11]
	v_mfma_f32_16x16x32_bf16 v[12:15], v[146:149], v[158:161], v[12:15]
	v_mfma_f32_16x16x32_bf16 v[16:19], v[146:149], v[162:165], v[16:19]
	v_mfma_f32_16x16x32_bf16 v[20:23], v[146:149], v[166:169], v[20:23]
	v_mfma_f32_16x16x32_bf16 v[24:27], v[150:153], v[154:157], v[24:27]
	v_mfma_f32_16x16x32_bf16 v[130:133], v[150:153], v[158:161], v[130:133]
	v_mfma_f32_16x16x32_bf16 v[134:137], v[150:153], v[162:165], v[134:137]
	v_mfma_f32_16x16x32_bf16 v[194:197], v[150:153], v[166:169], v[194:197]
	s_waitcnt lgkmcnt(0)
	v_mfma_f32_16x16x32_bf16 v[8:11], v[170:173], v[178:181], v[8:11]
	v_mfma_f32_16x16x32_bf16 v[12:15], v[170:173], v[182:185], v[12:15]
	v_mfma_f32_16x16x32_bf16 v[16:19], v[170:173], v[186:189], v[16:19]
	v_mfma_f32_16x16x32_bf16 v[20:23], v[170:173], v[190:193], v[20:23]
	v_mfma_f32_16x16x32_bf16 v[24:27], v[174:177], v[178:181], v[24:27]
	v_mfma_f32_16x16x32_bf16 v[130:133], v[174:177], v[182:185], v[130:133]
	v_mfma_f32_16x16x32_bf16 v[134:137], v[174:177], v[186:189], v[134:137]
	v_mfma_f32_16x16x32_bf16 v[194:197], v[174:177], v[190:193], v[194:197]
	s_waitcnt vmcnt(12)
	ds_write_b128 v206, v[34:37]
	ds_write_b128 v206, v[38:41] offset:1152
	ds_write_b128 v206, v[42:45] offset:2304
	ds_write_b128 v206, v[46:49] offset:3456
	ds_write_b128 v206, v[50:53] offset:4608
	ds_write_b128 v206, v[54:57] offset:5760
	ds_write_b128 v206, v[58:61] offset:6912
	ds_write_b128 v207, v[62:65]
	ds_write_b128 v207, v[66:69] offset:1152
	ds_write_b128 v207, v[70:73] offset:2304
	ds_write_b128 v207, v[74:77] offset:3456
	ds_write_b128 v207, v[78:81] offset:4608
	ds_read_b128 v[146:149], v208 offset:0
	ds_read_b128 v[150:153], v208 offset:2304
	ds_read_b128 v[154:157], v208 offset:4608
	ds_read_b128 v[158:161], v226
	ds_read_b128 v[162:165], v209 offset:1152
	ds_read_b128 v[166:169], v209 offset:3456
	ds_read_b128 v[170:173], v208 offset:64
	ds_read_b128 v[174:177], v208 offset:2368
	ds_read_b128 v[178:181], v208 offset:4672
	ds_read_b128 v[182:185], v226 offset:64
	ds_read_b128 v[186:189], v209 offset:1216
	ds_read_b128 v[190:193], v209 offset:3520
	s_waitcnt lgkmcnt(6)
	v_mfma_f32_16x16x32_bf16 v[8:11], v[146:149], v[154:157], v[8:11]
	v_mfma_f32_16x16x32_bf16 v[12:15], v[146:149], v[158:161], v[12:15]
	v_mfma_f32_16x16x32_bf16 v[16:19], v[146:149], v[162:165], v[16:19]
	v_mfma_f32_16x16x32_bf16 v[20:23], v[146:149], v[166:169], v[20:23]
	v_mfma_f32_16x16x32_bf16 v[24:27], v[150:153], v[154:157], v[24:27]
	v_mfma_f32_16x16x32_bf16 v[130:133], v[150:153], v[158:161], v[130:133]
	v_mfma_f32_16x16x32_bf16 v[134:137], v[150:153], v[162:165], v[134:137]
	v_mfma_f32_16x16x32_bf16 v[194:197], v[150:153], v[166:169], v[194:197]
	s_waitcnt lgkmcnt(0)
	v_mfma_f32_16x16x32_bf16 v[8:11], v[170:173], v[178:181], v[8:11]
	v_mfma_f32_16x16x32_bf16 v[12:15], v[170:173], v[182:185], v[12:15]
	v_mfma_f32_16x16x32_bf16 v[16:19], v[170:173], v[186:189], v[16:19]
	v_mfma_f32_16x16x32_bf16 v[20:23], v[170:173], v[190:193], v[20:23]
	v_mfma_f32_16x16x32_bf16 v[24:27], v[174:177], v[178:181], v[24:27]
	v_mfma_f32_16x16x32_bf16 v[130:133], v[174:177], v[182:185], v[130:133]
	v_mfma_f32_16x16x32_bf16 v[134:137], v[174:177], v[186:189], v[134:137]
	v_mfma_f32_16x16x32_bf16 v[194:197], v[174:177], v[190:193], v[194:197]
	s_waitcnt vmcnt(0)
; #define LAS __attribute__((address_space(3)))
; #define MFMA16(a, b, c) __builtin_amdgcn_mfma_f32_16x16x32_bf16((a), (b), (c), 0, 0, 0)
; __device__ __forceinline__ void sample_out_block(LAS unsigned char* lds, const bf16_t* A, const bf16_t* Bt, int K, bf16_t* xb, float* sspart, int blk, int tid) {
;     ...
;                     for (int nt = 0; nt < 4; ++nt) acc[ra][nt] = MFMA16(af[s][ra], bf[s][nt], acc[ra][nt]);
; #pragma unroll
;             for (int s = 0; s < 2; ++s) {
; #pragma unroll
;                 for (int ra = 0; ra < 2; ++ra) af[s][ra] = afn[s][ra];
; #pragma unroll
;                 for (int nt = 0; nt < 4; ++nt) bf[s][nt] = bfn[s][nt];
;             }
;         }
;     }
;     LAS f32x4* part = (LAS f32x4*)lds;
; #pragma unroll
;     for (int ra = 0; ra < 2; ++ra)
; #pragma unroll
;         for (int nt = 0; nt < 4; ++nt) part[(wave * 8 + ra * 4 + nt) * 64 + lane] = acc[ra][nt];
;     __syncthreads();
;     if (wave < 2) {
;         const int ra = wave;
;         f32x4 sum[4];
; #pragma unroll
;         for (int nt = 0; nt < 4; ++nt) {
;             sum[nt] = part[(0 * 8 + ra * 4 + nt) * 64 + lane];
; #pragma unroll
;             for (int w = 1; w < 8; ++w) sum[nt] += part[(w * 8 + ra * 4 + nt) * 64 + lane];
	ds_write_b128 v206, v[82:85]
	ds_write_b128 v206, v[86:89] offset:1152
	ds_write_b128 v206, v[90:93] offset:2304
	ds_write_b128 v206, v[94:97] offset:3456
	ds_write_b128 v206, v[98:101] offset:4608
	ds_write_b128 v206, v[102:105] offset:5760
	ds_write_b128 v206, v[106:109] offset:6912
	ds_write_b128 v207, v[110:113]
	ds_write_b128 v207, v[114:117] offset:1152
	ds_write_b128 v207, v[118:121] offset:2304
	ds_write_b128 v207, v[122:125] offset:3456
	ds_write_b128 v207, v[126:129] offset:4608
	ds_read_b128 v[146:149], v208 offset:0
	ds_read_b128 v[150:153], v208 offset:2304
	ds_read_b128 v[154:157], v208 offset:4608
	ds_read_b128 v[158:161], v226
	ds_read_b128 v[162:165], v209 offset:1152
	ds_read_b128 v[166:169], v209 offset:3456
	ds_read_b128 v[170:173], v208 offset:64
	ds_read_b128 v[174:177], v208 offset:2368
	ds_read_b128 v[178:181], v208 offset:4672
	ds_read_b128 v[182:185], v226 offset:64
	ds_read_b128 v[186:189], v209 offset:1216
	ds_read_b128 v[190:193], v209 offset:3520
	s_waitcnt lgkmcnt(6)
	v_mfma_f32_16x16x32_bf16 v[8:11], v[146:149], v[154:157], v[8:11]
	v_mfma_f32_16x16x32_bf16 v[12:15], v[146:149], v[158:161], v[12:15]
	v_mfma_f32_16x16x32_bf16 v[16:19], v[146:149], v[162:165], v[16:19]
	v_mfma_f32_16x16x32_bf16 v[20:23], v[146:149], v[166:169], v[20:23]
	v_mfma_f32_16x16x32_bf16 v[24:27], v[150:153], v[154:157], v[24:27]
	v_mfma_f32_16x16x32_bf16 v[130:133], v[150:153], v[158:161], v[130:133]
	v_mfma_f32_16x16x32_bf16 v[134:137], v[150:153], v[162:165], v[134:137]
	v_mfma_f32_16x16x32_bf16 v[194:197], v[150:153], v[166:169], v[194:197]
	s_waitcnt lgkmcnt(0)
	v_mfma_f32_16x16x32_bf16 v[8:11], v[170:173], v[178:181], v[8:11]
	v_mfma_f32_16x16x32_bf16 v[12:15], v[170:173], v[182:185], v[12:15]
	v_mfma_f32_16x16x32_bf16 v[16:19], v[170:173], v[186:189], v[16:19]
	v_mfma_f32_16x16x32_bf16 v[20:23], v[170:173], v[190:193], v[20:23]
	v_mfma_f32_16x16x32_bf16 v[24:27], v[174:177], v[178:181], v[24:27]
	v_mfma_f32_16x16x32_bf16 v[130:133], v[174:177], v[182:185], v[130:133]
	v_mfma_f32_16x16x32_bf16 v[134:137], v[174:177], v[186:189], v[134:137]
	v_mfma_f32_16x16x32_bf16 v[194:197], v[174:177], v[190:193], v[194:197]
	s_nop 7
	s_nop 7
	ds_write_b128 v32, v[8:11]
	ds_write_b128 v32, v[12:15] offset:1024
	ds_write_b128 v32, v[16:19] offset:2048
	ds_write_b128 v32, v[20:23] offset:3072
	ds_write_b128 v32, v[24:27] offset:4096
	ds_write_b128 v32, v[130:133] offset:5120
	ds_write_b128 v32, v[134:137] offset:6144
	ds_write_b128 v32, v[194:197] offset:7168
	s_waitcnt lgkmcnt(0)
	s_barrier
	s_and_saveexec_b64 s[10:11], s[6:7]
	s_cbranch_execz .LBB0_541
	ds_read_b128 v[8:11], v33
	ds_read_b128 v[12:15], v33 offset:8192
	s_lshl_b32 s80, s35, 1
	v_lshl_add_u64 v[28:29], v[6:7], 0, s[80:81]
	s_lshl_b32 s12, s26, 2
	s_add_u32 s12, s22, s12
	s_waitcnt lgkmcnt(0)
	v_pk_add_f32 v[14:15], v[10:11], v[14:15]
	v_pk_add_f32 v[12:13], v[8:9], v[12:13]
	ds_read_b128 v[8:11], v33 offset:16384
	s_addc_u32 s13, s23, 0
	s_waitcnt lgkmcnt(0)
	v_pk_add_f32 v[14:15], v[14:15], v[10:11]
	v_pk_add_f32 v[12:13], v[12:13], v[8:9]
	ds_read_b128 v[8:11], v33 offset:24576
	s_waitcnt lgkmcnt(0)
	v_pk_add_f32 v[14:15], v[14:15], v[10:11]
	v_pk_add_f32 v[12:13], v[12:13], v[8:9]
	ds_read_b128 v[8:11], v33 offset:32768
	s_waitcnt lgkmcnt(0)
	v_pk_add_f32 v[14:15], v[14:15], v[10:11]
	v_pk_add_f32 v[12:13], v[12:13], v[8:9]
	ds_read_b128 v[8:11], v33 offset:40960
	s_waitcnt lgkmcnt(0)
	v_pk_add_f32 v[14:15], v[14:15], v[10:11]
	v_pk_add_f32 v[12:13], v[12:13], v[8:9]
	ds_read_b128 v[8:11], v33 offset:49152
	s_waitcnt lgkmcnt(0)
	v_pk_add_f32 v[14:15], v[14:15], v[10:11]
	v_pk_add_f32 v[16:17], v[12:13], v[8:9]
	ds_read_b128 v[8:11], v33 offset:57344
	s_waitcnt lgkmcnt(0)
	v_pk_add_f32 v[12:13], v[14:15], v[10:11]
	v_pk_add_f32 v[20:21], v[16:17], v[8:9]
	ds_read_b128 v[8:11], v33 offset:1024
	ds_read_b128 v[14:17], v33 offset:9216
	s_waitcnt lgkmcnt(0)
	v_pk_add_f32 v[16:17], v[10:11], v[16:17]
	v_pk_add_f32 v[14:15], v[8:9], v[14:15]
	ds_read_b128 v[8:11], v33 offset:17408
	s_waitcnt lgkmcnt(0)
	v_pk_add_f32 v[16:17], v[16:17], v[10:11]
	v_pk_add_f32 v[14:15], v[14:15], v[8:9]
	ds_read_b128 v[8:11], v33 offset:25600
	s_waitcnt lgkmcnt(0)
	v_pk_add_f32 v[16:17], v[16:17], v[10:11]
	v_pk_add_f32 v[14:15], v[14:15], v[8:9]
	ds_read_b128 v[8:11], v33 offset:33792
	s_waitcnt lgkmcnt(0)
	v_pk_add_f32 v[16:17], v[16:17], v[10:11]
	v_pk_add_f32 v[14:15], v[14:15], v[8:9]
	ds_read_b128 v[8:11], v33 offset:41984
	s_waitcnt lgkmcnt(0)
	v_pk_add_f32 v[16:17], v[16:17], v[10:11]
	v_pk_add_f32 v[14:15], v[14:15], v[8:9]
	ds_read_b128 v[8:11], v33 offset:50176
	s_waitcnt lgkmcnt(0)
	v_pk_add_f32 v[16:17], v[16:17], v[10:11]
	v_pk_add_f32 v[14:15], v[14:15], v[8:9]
	ds_read_b128 v[8:11], v33 offset:58368
	s_waitcnt lgkmcnt(0)
	v_pk_add_f32 v[18:19], v[16:17], v[10:11]
	v_pk_add_f32 v[26:27], v[14:15], v[8:9]
	ds_read_b128 v[8:11], v33 offset:2048
	ds_read_b128 v[14:17], v33 offset:10240
	s_waitcnt lgkmcnt(0)
	v_pk_add_f32 v[16:17], v[10:11], v[16:17]
	v_pk_add_f32 v[14:15], v[8:9], v[14:15]
	ds_read_b128 v[8:11], v33 offset:18432
	s_waitcnt lgkmcnt(0)
	v_pk_add_f32 v[16:17], v[16:17], v[10:11]
	v_pk_add_f32 v[14:15], v[14:15], v[8:9]
	ds_read_b128 v[8:11], v33 offset:26624
	s_waitcnt lgkmcnt(0)
	v_pk_add_f32 v[16:17], v[16:17], v[10:11]
	v_pk_add_f32 v[14:15], v[14:15], v[8:9]
	ds_read_b128 v[8:11], v33 offset:34816
	s_waitcnt lgkmcnt(0)
	v_pk_add_f32 v[16:17], v[16:17], v[10:11]
	v_pk_add_f32 v[14:15], v[14:15], v[8:9]
	ds_read_b128 v[8:11], v33 offset:43008
	s_waitcnt lgkmcnt(0)
	v_pk_add_f32 v[16:17], v[16:17], v[10:11]
	v_pk_add_f32 v[14:15], v[14:15], v[8:9]
	ds_read_b128 v[8:11], v33 offset:51200
	s_waitcnt lgkmcnt(0)
; __device__ __forceinline__ float bf1(bf16_t h) { return __uint_as_float((unsigned)h << 16); }
; __device__ __forceinline__ bf16_t f2bf(float f) { return (bf16_t)(pk2(f, 0.f) & 0xffffu); }
; __device__ __forceinline__ void sample_out_block(LAS unsigned char* lds, const bf16_t* A, const bf16_t* Bt, int K, bf16_t* xb, float* sspart, int blk, int tid) {
;     ...
;             for (int w = 1; w < 8; ++w) sum[nt] += part[(w * 8 + ra * 4 + nt) * 64 + lane];
;         }
;         float ss[4] = {0.f, 0.f, 0.f, 0.f};
; #pragma unroll
;         for (int j = 0; j < 4; ++j)
; #pragma unroll
;             for (int nt = 0; nt < 4; ++nt) {
;                 bf16_t* xp = xb + (size_t)(r0 + 16 * ra + 4 * g + j) * 2048 + 64 * cg + 16 * nt + l15;
;                 const bf16_t nv = f2bf(bf1(*xp) + sum[nt][j]);
;                 *xp = nv; const float r = bf1(nv); ss[j] += r * r;
;             }
; #pragma unroll
;         for (int j = 0; j < 4; ++j) {
;             float s = ss[j];
;             s += __shfl_xor(s, 1); s += __shfl_xor(s, 2); s += __shfl_xor(s, 4); s += __shfl_xor(s, 8);
;             if (l15 == 0) sspart[(size_t)(r0 + 16 * ra + 4 * g + j) * 32 + cg] = s;
	v_pk_add_f32 v[16:17], v[16:17], v[10:11]
	v_pk_add_f32 v[14:15], v[14:15], v[8:9]
	ds_read_b128 v[8:11], v33 offset:59392
	s_waitcnt lgkmcnt(0)
	v_pk_add_f32 v[16:17], v[16:17], v[10:11]
	v_pk_add_f32 v[24:25], v[14:15], v[8:9]
	ds_read_b128 v[8:11], v33 offset:3072
	ds_read_b128 v[34:37], v33 offset:11264
	s_waitcnt lgkmcnt(0)
	v_pk_add_f32 v[14:15], v[10:11], v[36:37]
	v_pk_add_f32 v[22:23], v[8:9], v[34:35]
	ds_read_b128 v[8:11], v33 offset:19456
	ds_read_b128 v[34:37], v33 offset:60416
	s_waitcnt lgkmcnt(1)
	v_pk_add_f32 v[14:15], v[14:15], v[10:11]
	v_pk_add_f32 v[22:23], v[22:23], v[8:9]
	ds_read_b128 v[8:11], v33 offset:27648
	s_waitcnt lgkmcnt(0)
	v_pk_add_f32 v[14:15], v[14:15], v[10:11]
	v_pk_add_f32 v[22:23], v[22:23], v[8:9]
	ds_read_b128 v[8:11], v33 offset:35840
	s_waitcnt lgkmcnt(0)
	v_pk_add_f32 v[14:15], v[14:15], v[10:11]
	v_pk_add_f32 v[22:23], v[22:23], v[8:9]
	ds_read_b128 v[8:11], v33 offset:44032
	s_waitcnt lgkmcnt(0)
	v_pk_add_f32 v[14:15], v[14:15], v[10:11]
	v_pk_add_f32 v[22:23], v[22:23], v[8:9]
	ds_read_b128 v[8:11], v33 offset:52224
	s_waitcnt lgkmcnt(0)
	v_pk_add_f32 v[10:11], v[14:15], v[10:11]
	v_pk_add_f32 v[14:15], v[22:23], v[8:9]
	v_pk_add_f32 v[8:9], v[10:11], v[36:37]
	v_add_u32_e32 v10, s27, v31
	v_ashrrev_i32_e32 v11, 31, v10
	v_pk_add_f32 v[22:23], v[14:15], v[34:35]
	v_lshlrev_b64 v[14:15], 12, v[10:11]
	v_lshl_add_u64 v[14:15], v[28:29], 0, v[14:15]
	global_load_ushort v0, v[14:15], off
	s_waitcnt vmcnt(0)
	v_lshlrev_b32_e32 v0, 16, v0
	v_add_f32_e32 v0, v20, v0
	v_cvt_pk_bf16_f32 v0, v0, s0
	global_store_short v[14:15], v0, off
	v_lshlrev_b32_e32 v20, 16, v0
	global_load_ushort v0, v[14:15], off offset:32
	s_waitcnt vmcnt(0)
	v_lshlrev_b32_e32 v0, 16, v0
	v_add_f32_e32 v0, v26, v0
	v_cvt_pk_bf16_f32 v0, v0, s0
	global_store_short v[14:15], v0, off offset:32
	v_lshlrev_b32_e32 v0, 16, v0
	v_mul_f32_e32 v0, v0, v0
	v_fmac_f32_e32 v0, v20, v20
	global_load_ushort v20, v[14:15], off offset:64
	s_waitcnt vmcnt(0)
	v_lshlrev_b32_e32 v20, 16, v20
	v_add_f32_e32 v20, v24, v20
	v_cvt_pk_bf16_f32 v20, v20, s0
	global_store_short v[14:15], v20, off offset:64
	v_lshlrev_b32_e32 v20, 16, v20
	v_fmac_f32_e32 v0, v20, v20
	global_load_ushort v20, v[14:15], off offset:96
	s_waitcnt vmcnt(0)
	v_lshlrev_b32_e32 v20, 16, v20
	v_add_f32_e32 v20, v22, v20
	v_cvt_pk_bf16_f32 v20, v20, s0
	global_store_short v[14:15], v20, off offset:96
	v_lshlrev_b32_e32 v14, 16, v20
	v_fmac_f32_e32 v0, v14, v14
	v_or_b32_e32 v14, 1, v10
	v_ashrrev_i32_e32 v15, 31, v14
	v_lshlrev_b64 v[34:35], 12, v[14:15]
	v_lshl_add_u64 v[36:37], v[28:29], 0, v[34:35]
	global_load_ushort v20, v[36:37], off
	s_waitcnt vmcnt(0)
	v_lshlrev_b32_e32 v20, 16, v20
	v_add_f32_e32 v20, v21, v20
	v_cvt_pk_bf16_f32 v26, v20, s0
	global_load_ushort v20, v[36:37], off offset:32
	s_waitcnt vmcnt(0)
	v_lshlrev_b32_e32 v20, 16, v20
	v_add_f32_e32 v20, v27, v20
	v_cvt_pk_bf16_f32 v27, v20, s0
	global_load_ushort v20, v[36:37], off offset:64
	s_waitcnt vmcnt(0)
	v_lshlrev_b32_e32 v20, 16, v20
	v_add_f32_e32 v20, v25, v20
	v_cvt_pk_bf16_f32 v34, v20, s0
	global_load_ushort v20, v[36:37], off offset:96
	s_waitcnt vmcnt(0)
	v_lshlrev_b32_e32 v20, 16, v20
	v_add_f32_e32 v20, v23, v20
	v_cvt_pk_bf16_f32 v35, v20, s0
	v_or_b32_e32 v20, 2, v10
	v_ashrrev_i32_e32 v21, 31, v20
	v_lshlrev_b64 v[22:23], 12, v[20:21]
	v_lshl_add_u64 v[22:23], v[28:29], 0, v[22:23]
	global_load_ushort v24, v[22:23], off
	s_waitcnt vmcnt(0)
	v_lshlrev_b32_e32 v24, 16, v24
	v_add_f32_e32 v12, v12, v24
	global_load_ushort v24, v[22:23], off offset:32
	v_cvt_pk_bf16_f32 v12, v12, s0
	global_store_short v[22:23], v12, off
	global_store_short v[36:37], v26, off
	global_store_short v[36:37], v27, off offset:32
	global_store_short v[36:37], v34, off offset:64
	global_store_short v[36:37], v35, off offset:96
	v_xor_b32_e32 v36, 8, v215
	s_waitcnt vmcnt(5)
	v_lshlrev_b32_e32 v24, 16, v24
	v_add_f32_e32 v18, v18, v24
	global_load_ushort v24, v[22:23], off offset:64
	v_cvt_pk_bf16_f32 v18, v18, s0
	global_store_short v[22:23], v18, off offset:32
	s_waitcnt vmcnt(1)
	v_lshlrev_b32_e32 v24, 16, v24
	v_add_f32_e32 v16, v16, v24
	global_load_ushort v24, v[22:23], off offset:96
	v_cvt_pk_bf16_f32 v16, v16, s0
	global_store_short v[22:23], v16, off offset:64
	s_waitcnt vmcnt(1)
	v_lshlrev_b32_e32 v24, 16, v24
	v_add_f32_e32 v8, v8, v24
	v_cvt_pk_bf16_f32 v8, v8, s0
	global_store_short v[22:23], v8, off offset:96
	v_or_b32_e32 v22, 3, v10
	v_ashrrev_i32_e32 v23, 31, v22
	v_lshlrev_b64 v[24:25], 12, v[22:23]
	v_lshl_add_u64 v[24:25], v[28:29], 0, v[24:25]
	global_load_ushort v28, v[24:25], off
	s_waitcnt vmcnt(0)
	v_lshlrev_b32_e32 v28, 16, v28
	v_add_f32_e32 v13, v13, v28
	global_load_ushort v28, v[24:25], off offset:32
	v_cvt_pk_bf16_f32 v13, v13, s0
	global_store_short v[24:25], v13, off
	s_waitcnt vmcnt(1)
	v_lshlrev_b32_e32 v28, 16, v28
	v_add_f32_e32 v19, v19, v28
	global_load_ushort v28, v[24:25], off offset:64
	v_cvt_pk_bf16_f32 v19, v19, s0
	global_store_short v[24:25], v19, off offset:32
	s_waitcnt vmcnt(1)
	v_lshlrev_b32_e32 v28, 16, v28
	v_add_f32_e32 v17, v17, v28
	global_load_ushort v28, v[24:25], off offset:96
	v_cvt_pk_bf16_f32 v17, v17, s0
	global_store_short v[24:25], v17, off offset:64
	s_waitcnt vmcnt(1)
	v_lshlrev_b32_e32 v28, 16, v28
	v_add_f32_e32 v9, v9, v28
	v_cvt_pk_bf16_f32 v9, v9, s0
	global_store_short v[24:25], v9, off offset:96
	v_and_b32_e32 v25, 64, v215
	v_xor_b32_e32 v24, 1, v215
	v_add_u32_e32 v29, 64, v25
	v_cmp_lt_i32_e32 vcc, v24, v29
	v_xor_b32_e32 v25, 2, v215
	v_xor_b32_e32 v28, 4, v215
	v_cndmask_b32_e32 v24, v215, v24, vcc
	v_cmp_lt_i32_e32 vcc, v25, v29
	v_lshlrev_b32_e32 v24, 2, v24
	s_nop 0
	v_cndmask_b32_e32 v25, v215, v25, vcc
	v_cmp_lt_i32_e32 vcc, v28, v29
	v_lshlrev_b32_e32 v25, 2, v25
	s_nop 0
	v_cndmask_b32_e32 v28, v215, v28, vcc
	v_cmp_lt_i32_e32 vcc, v36, v29
	v_lshlrev_b32_e32 v28, 2, v28
	s_nop 0
	v_cndmask_b32_e32 v29, v215, v36, vcc
	ds_bpermute_b32 v36, v24, v0
	v_lshlrev_b32_e32 v29, 2, v29
	s_waitcnt lgkmcnt(0)
	v_add_f32_e32 v0, v0, v36
	ds_bpermute_b32 v36, v25, v0
	s_waitcnt lgkmcnt(0)
	v_add_f32_e32 v0, v0, v36
	ds_bpermute_b32 v36, v28, v0
	s_waitcnt lgkmcnt(0)
	v_add_f32_e32 v0, v0, v36
	ds_bpermute_b32 v36, v29, v0
	s_and_saveexec_b64 s[26:27], s[8:9]
	s_cbranch_execz .LBB0_545
	v_lshlrev_b64 v[10:11], 7, v[10:11]
	v_lshl_add_u64 v[10:11], s[12:13], 0, v[10:11]
	s_waitcnt lgkmcnt(0)
	v_add_f32_e32 v0, v0, v36
	global_store_dword v[10:11], v0, off

; #define MFMA16(a, b, c) __builtin_amdgcn_mfma_f32_16x16x32_bf16((a), (b), (c), 0, 0, 0)
; __device__ __forceinline__ void sample_out_block(LAS unsigned char* lds, const bf16_t* A, const bf16_t* Bt, int K, bf16_t* xb, float* sspart, int blk, int tid) {
;     ...
;     {
;         const bf16_t* ap = A + (size_t)(r0 + l15) * K + wave * kq + 8 * g;
;         const bf16_t* bp = Bt + (size_t)(64 * cg + l15) * K + wave * kq + 8 * g;
;         bf16x8 af[2][2], bf[2][4], afn[2][2], bfn[2][4];
; #pragma unroll
;         for (int s = 0; s < 2; ++s) {
; #pragma unroll
;             for (int ra = 0; ra < 2; ++ra) af[s][ra] = *(const bf16x8*)(ap + (size_t)(16 * ra) * K + 32 * s);
; #pragma unroll
;             for (int nt = 0; nt < 4; ++nt) bf[s][nt] = *(const bf16x8*)(bp + (size_t)(16 * nt) * K + 32 * s);
;         }
;         for (int k0 = 0; k0 < kq; k0 += 64) {
;             const int k1 = (k0 + 64 < kq) ? k0 + 64 : k0;
; #pragma unroll
;             for (int s = 0; s < 2; ++s) {
; #pragma unroll
;                 for (int ra = 0; ra < 2; ++ra) afn[s][ra] = *(const bf16x8*)(ap + (size_t)(16 * ra) * K + k1 + 32 * s);
; #pragma unroll
;                 for (int nt = 0; nt < 4; ++nt) bfn[s][nt] = *(const bf16x8*)(bp + (size_t)(16 * nt) * K + k1 + 32 * s);
;             }
; #pragma unroll
;             for (int s = 0; s < 2; ++s)
; #pragma unroll
;                 for (int ra = 0; ra < 2; ++ra)
; #pragma unroll
;                     for (int nt = 0; nt < 4; ++nt) acc[ra][nt] = MFMA16(af[s][ra], bf[s][nt], acc[ra][nt]);
.LBB0_1165:
	s_and_b32 s21, s26, 0xffffffe0
	s_addk_i32 s21, 0x2000
	s_and_b32 s20, s26, 31
	v_or_b32_e32 v8, s21, v30
	v_ashrrev_i32_e32 v9, 31, v8
	s_lshl_b32 s27, s20, 6
	v_lshlrev_b64 v[8:9], 12, v[8:9]
	v_or_b32_e32 v0, s27, v30
	v_lshl_add_u64 v[10:11], v[2:3], 0, v[8:9]
	v_lshlrev_b32_e32 v0, 12, v0
	v_lshl_add_u64 v[16:17], v[4:5], 0, v[0:1]
	v_add_co_u32_e32 v8, vcc, 0x10000, v10
	s_mov_b64 s[8:9], vcc
	v_add_co_u32_e32 v12, vcc, 0x10000, v16
	v_readfirstlane_b32 s36, v139
	s_lshr_b32 s36, s36, 6
	s_and_b32 s37, s26, 0xffffffe0
	s_addk_i32 s37, 0x2000
	s_and_b32 s38, s26, 31
	s_lshl_b32 s38, s38, 6
	s_lshl_b32 s39, s37, 12
	s_mul_i32 s40, s36, 0x200
	s_add_u32 s42, s18, s39
	s_addc_u32 s43, s19, 0
	s_add_u32 s42, s42, s40
	s_addc_u32 s43, s43, 0
	s_lshl_b32 s41, s24, 1
	s_lshl_b32 s39, s38, 12
	s_add_u32 s44, s22, s41
	s_addc_u32 s45, s23, 0
	s_add_u32 s44, s44, s39
	s_addc_u32 s45, s45, 0
	s_add_u32 s44, s44, s40
	s_addc_u32 s45, s45, 0
	v_lshrrev_b32_e32 v227, 3, v215
	v_and_b32_e32 v228, 7, v215
	v_lshlrev_b32_e32 v198, 12, v227
	v_lshl_add_u32 v198, v228, 4, v198
	v_add_u32_e32 v199, 0x8000, v198
	v_add_u32_e32 v200, 0x10000, v198
	v_add_u32_e32 v201, 0x18000, v198
	v_add_u32_e32 v202, 0x20000, v198
	v_add_u32_e32 v203, 0x28000, v198
	v_add_u32_e32 v204, 0x30000, v198
	v_add_u32_e32 v205, 0x38000, v198
	s_lshl_b32 s46, s36, 13
	s_mul_i32 s47, s36, 0x1800
	s_add_i32 s47, s47, 0x10000
	v_mul_u32_u24_e32 v206, 0x90, v227
	v_lshl_add_u32 v206, v228, 4, v206
	v_add_u32_e32 v207, s47, v206
	v_add_u32_e32 v206, s46, v206
	v_and_b32_e32 v227, 15, v215
	v_lshrrev_b32_e32 v228, 4, v215
	v_mul_u32_u24_e32 v208, 0x90, v227
	v_lshl_add_u32 v208, v228, 4, v208
	v_add_u32_e32 v209, s47, v208
	v_add_u32_e32 v208, s46, v208
	v_add_u32_e32 v226, 0x1b00, v208
	v_subrev_u32_e32 v228, 0x480, v209
	v_cmp_gt_u32_e32 vcc, 8, v227
	v_cndmask_b32_e32 v226, v228, v226, vcc
	global_load_dwordx4 v[34:37], v198, s[42:43]
	global_load_dwordx4 v[38:41], v199, s[42:43]
	global_load_dwordx4 v[42:45], v200, s[42:43]
	global_load_dwordx4 v[46:49], v201, s[42:43]
	global_load_dwordx4 v[50:53], v198, s[44:45]
	global_load_dwordx4 v[54:57], v199, s[44:45]
	global_load_dwordx4 v[58:61], v200, s[44:45]
	global_load_dwordx4 v[62:65], v201, s[44:45]
	global_load_dwordx4 v[66:69], v202, s[44:45]
	global_load_dwordx4 v[70:73], v203, s[44:45]
	global_load_dwordx4 v[74:77], v204, s[44:45]
	global_load_dwordx4 v[78:81], v205, s[44:45]
	global_load_dwordx4 v[82:85], v198, s[42:43] offset:128
	global_load_dwordx4 v[86:89], v199, s[42:43] offset:128
	global_load_dwordx4 v[90:93], v200, s[42:43] offset:128
	global_load_dwordx4 v[94:97], v201, s[42:43] offset:128
	global_load_dwordx4 v[98:101], v198, s[44:45] offset:128
	global_load_dwordx4 v[102:105], v199, s[44:45] offset:128
	global_load_dwordx4 v[106:109], v200, s[44:45] offset:128
	global_load_dwordx4 v[110:113], v201, s[44:45] offset:128
	global_load_dwordx4 v[114:117], v202, s[44:45] offset:128
	global_load_dwordx4 v[118:121], v203, s[44:45] offset:128
	global_load_dwordx4 v[122:125], v204, s[44:45] offset:128
	global_load_dwordx4 v[126:129], v205, s[44:45] offset:128
	s_waitcnt vmcnt(12)
	ds_write_b128 v206, v[34:37]
	ds_write_b128 v206, v[38:41] offset:1152
	ds_write_b128 v206, v[42:45] offset:2304
	ds_write_b128 v206, v[46:49] offset:3456
	ds_write_b128 v206, v[50:53] offset:4608
	ds_write_b128 v206, v[54:57] offset:5760
	ds_write_b128 v206, v[58:61] offset:6912
	ds_write_b128 v207, v[62:65]
	ds_write_b128 v207, v[66:69] offset:1152
	ds_write_b128 v207, v[70:73] offset:2304
	ds_write_b128 v207, v[74:77] offset:3456
	ds_write_b128 v207, v[78:81] offset:4608
	global_load_dwordx4 v[34:37], v198, s[42:43] offset:256
	global_load_dwordx4 v[38:41], v199, s[42:43] offset:256
	global_load_dwordx4 v[42:45], v200, s[42:43] offset:256
	global_load_dwordx4 v[46:49], v201, s[42:43] offset:256
	global_load_dwordx4 v[50:53], v198, s[44:45] offset:256
	global_load_dwordx4 v[54:57], v199, s[44:45] offset:256
	global_load_dwordx4 v[58:61], v200, s[44:45] offset:256
	global_load_dwordx4 v[62:65], v201, s[44:45] offset:256
	global_load_dwordx4 v[66:69], v202, s[44:45] offset:256
	global_load_dwordx4 v[70:73], v203, s[44:45] offset:256
	global_load_dwordx4 v[74:77], v204, s[44:45] offset:256
	global_load_dwordx4 v[78:81], v205, s[44:45] offset:256
	ds_read_b128 v[146:149], v208 offset:0
	ds_read_b128 v[150:153], v208 offset:2304
	ds_read_b128 v[154:157], v208 offset:4608
	ds_read_b128 v[158:161], v226
	ds_read_b128 v[162:165], v209 offset:1152
	ds_read_b128 v[166:169], v209 offset:3456
	ds_read_b128 v[170:173], v208 offset:64
	ds_read_b128 v[174:177], v208 offset:2368
	ds_read_b128 v[178:181], v208 offset:4672
	ds_read_b128 v[182:185], v226 offset:64
	ds_read_b128 v[186:189], v209 offset:1216
	ds_read_b128 v[190:193], v209 offset:3520
	s_waitcnt lgkmcnt(6)
	v_mfma_f32_16x16x32_bf16 v[8:11], v[146:149], v[154:157], 0
	v_mfma_f32_16x16x32_bf16 v[12:15], v[146:149], v[158:161], 0
	v_mfma_f32_16x16x32_bf16 v[16:19], v[146:149], v[162:165], 0
	v_mfma_f32_16x16x32_bf16 v[20:23], v[146:149], v[166:169], 0
	v_mfma_f32_16x16x32_bf16 v[24:27], v[150:153], v[154:157], 0
	v_mfma_f32_16x16x32_bf16 v[130:133], v[150:153], v[158:161], 0
	v_mfma_f32_16x16x32_bf16 v[134:137], v[150:153], v[162:165], 0
	v_mfma_f32_16x16x32_bf16 v[194:197], v[150:153], v[166:169], 0
	s_waitcnt lgkmcnt(0)
; #define MFMA16(a, b, c) __builtin_amdgcn_mfma_f32_16x16x32_bf16((a), (b), (c), 0, 0, 0)
; __device__ __forceinline__ void sample_out_block(LAS unsigned char* lds, const bf16_t* A, const bf16_t* Bt, int K, bf16_t* xb, float* sspart, int blk, int tid) {
;     ...
;         for (int k0 = 0; k0 < kq; k0 += 64) {
;             const int k1 = (k0 + 64 < kq) ? k0 + 64 : k0;
; #pragma unroll
;             for (int s = 0; s < 2; ++s) {
; #pragma unroll
;                 for (int ra = 0; ra < 2; ++ra) afn[s][ra] = *(const bf16x8*)(ap + (size_t)(16 * ra) * K + k1 + 32 * s);
; #pragma unroll
;                 for (int nt = 0; nt < 4; ++nt) bfn[s][nt] = *(const bf16x8*)(bp + (size_t)(16 * nt) * K + k1 + 32 * s);
;             }
; #pragma unroll
;             for (int s = 0; s < 2; ++s)
; #pragma unroll
;                 for (int ra = 0; ra < 2; ++ra)
; #pragma unroll
;                     for (int nt = 0; nt < 4; ++nt) acc[ra][nt] = MFMA16(af[s][ra], bf[s][nt], acc[ra][nt]);
	v_mfma_f32_16x16x32_bf16 v[8:11], v[170:173], v[178:181], v[8:11]
	v_mfma_f32_16x16x32_bf16 v[12:15], v[170:173], v[182:185], v[12:15]
	v_mfma_f32_16x16x32_bf16 v[16:19], v[170:173], v[186:189], v[16:19]
	v_mfma_f32_16x16x32_bf16 v[20:23], v[170:173], v[190:193], v[20:23]
	v_mfma_f32_16x16x32_bf16 v[24:27], v[174:177], v[178:181], v[24:27]
	v_mfma_f32_16x16x32_bf16 v[130:133], v[174:177], v[182:185], v[130:133]
	v_mfma_f32_16x16x32_bf16 v[134:137], v[174:177], v[186:189], v[134:137]
	v_mfma_f32_16x16x32_bf16 v[194:197], v[174:177], v[190:193], v[194:197]
	s_waitcnt vmcnt(12)
	ds_write_b128 v206, v[82:85]
	ds_write_b128 v206, v[86:89] offset:1152
	ds_write_b128 v206, v[90:93] offset:2304
	ds_write_b128 v206, v[94:97] offset:3456
	ds_write_b128 v206, v[98:101] offset:4608
	ds_write_b128 v206, v[102:105] offset:5760
	ds_write_b128 v206, v[106:109] offset:6912
	ds_write_b128 v207, v[110:113]
	ds_write_b128 v207, v[114:117] offset:1152
	ds_write_b128 v207, v[118:121] offset:2304
	ds_write_b128 v207, v[122:125] offset:3456
	ds_write_b128 v207, v[126:129] offset:4608
	global_load_dwordx4 v[82:85], v198, s[42:43] offset:384
	global_load_dwordx4 v[86:89], v199, s[42:43] offset:384
	global_load_dwordx4 v[90:93], v200, s[42:43] offset:384
	global_load_dwordx4 v[94:97], v201, s[42:43] offset:384
	global_load_dwordx4 v[98:101], v198, s[44:45] offset:384
	global_load_dwordx4 v[102:105], v199, s[44:45] offset:384
	global_load_dwordx4 v[106:109], v200, s[44:45] offset:384
	global_load_dwordx4 v[110:113], v201, s[44:45] offset:384
	global_load_dwordx4 v[114:117], v202, s[44:45] offset:384
	global_load_dwordx4 v[118:121], v203, s[44:45] offset:384
	global_load_dwordx4 v[122:125], v204, s[44:45] offset:384
	global_load_dwordx4 v[126:129], v205, s[44:45] offset:384
	ds_read_b128 v[146:149], v208 offset:0
	ds_read_b128 v[150:153], v208 offset:2304
	ds_read_b128 v[154:157], v208 offset:4608
	ds_read_b128 v[158:161], v226
	ds_read_b128 v[162:165], v209 offset:1152
	ds_read_b128 v[166:169], v209 offset:3456
	ds_read_b128 v[170:173], v208 offset:64
	ds_read_b128 v[174:177], v208 offset:2368
	ds_read_b128 v[178:181], v208 offset:4672
	ds_read_b128 v[182:185], v226 offset:64
	ds_read_b128 v[186:189], v209 offset:1216
	ds_read_b128 v[190:193], v209 offset:3520
	s_waitcnt lgkmcnt(6)
	v_mfma_f32_16x16x32_bf16 v[8:11], v[146:149], v[154:157], v[8:11]
	v_mfma_f32_16x16x32_bf16 v[12:15], v[146:149], v[158:161], v[12:15]
	v_mfma_f32_16x16x32_bf16 v[16:19], v[146:149], v[162:165], v[16:19]
	v_mfma_f32_16x16x32_bf16 v[20:23], v[146:149], v[166:169], v[20:23]
	v_mfma_f32_16x16x32_bf16 v[24:27], v[150:153], v[154:157], v[24:27]
	v_mfma_f32_16x16x32_bf16 v[130:133], v[150:153], v[158:161], v[130:133]
	v_mfma_f32_16x16x32_bf16 v[134:137], v[150:153], v[162:165], v[134:137]
	v_mfma_f32_16x16x32_bf16 v[194:197], v[150:153], v[166:169], v[194:197]
	s_waitcnt lgkmcnt(0)
	v_mfma_f32_16x16x32_bf16 v[8:11], v[170:173], v[178:181], v[8:11]
	v_mfma_f32_16x16x32_bf16 v[12:15], v[170:173], v[182:185], v[12:15]
	v_mfma_f32_16x16x32_bf16 v[16:19], v[170:173], v[186:189], v[16:19]
	v_mfma_f32_16x16x32_bf16 v[20:23], v[170:173], v[190:193], v[20:23]
	v_mfma_f32_16x16x32_bf16 v[24:27], v[174:177], v[178:181], v[24:27]
	v_mfma_f32_16x16x32_bf16 v[130:133], v[174:177], v[182:185], v[130:133]
	v_mfma_f32_16x16x32_bf16 v[134:137], v[174:177], v[186:189], v[134:137]
	v_mfma_f32_16x16x32_bf16 v[194:197], v[174:177], v[190:193], v[194:197]
	s_waitcnt vmcnt(12)
	ds_write_b128 v206, v[34:37]
	ds_write_b128 v206, v[38:41] offset:1152
	ds_write_b128 v206, v[42:45] offset:2304
	ds_write_b128 v206, v[46:49] offset:3456
	ds_write_b128 v206, v[50:53] offset:4608
	ds_write_b128 v206, v[54:57] offset:5760
	ds_write_b128 v206, v[58:61] offset:6912
	ds_write_b128 v207, v[62:65]
	ds_write_b128 v207, v[66:69] offset:1152
	ds_write_b128 v207, v[70:73] offset:2304
	ds_write_b128 v207, v[74:77] offset:3456
	ds_write_b128 v207, v[78:81] offset:4608
	ds_read_b128 v[146:149], v208 offset:0
	ds_read_b128 v[150:153], v208 offset:2304
	ds_read_b128 v[154:157], v208 offset:4608
	ds_read_b128 v[158:161], v226
	ds_read_b128 v[162:165], v209 offset:1152
	ds_read_b128 v[166:169], v209 offset:3456
	ds_read_b128 v[170:173], v208 offset:64
	ds_read_b128 v[174:177], v208 offset:2368
	ds_read_b128 v[178:181], v208 offset:4672
	ds_read_b128 v[182:185], v226 offset:64
	ds_read_b128 v[186:189], v209 offset:1216
	ds_read_b128 v[190:193], v209 offset:3520
	s_waitcnt lgkmcnt(6)
	v_mfma_f32_16x16x32_bf16 v[8:11], v[146:149], v[154:157], v[8:11]
	v_mfma_f32_16x16x32_bf16 v[12:15], v[146:149], v[158:161], v[12:15]
	v_mfma_f32_16x16x32_bf16 v[16:19], v[146:149], v[162:165], v[16:19]
	v_mfma_f32_16x16x32_bf16 v[20:23], v[146:149], v[166:169], v[20:23]
	v_mfma_f32_16x16x32_bf16 v[24:27], v[150:153], v[154:157], v[24:27]
	v_mfma_f32_16x16x32_bf16 v[130:133], v[150:153], v[158:161], v[130:133]
	v_mfma_f32_16x16x32_bf16 v[134:137], v[150:153], v[162:165], v[134:137]
	v_mfma_f32_16x16x32_bf16 v[194:197], v[150:153], v[166:169], v[194:197]
	s_waitcnt lgkmcnt(0)
	v_mfma_f32_16x16x32_bf16 v[8:11], v[170:173], v[178:181], v[8:11]
	v_mfma_f32_16x16x32_bf16 v[12:15], v[170:173], v[182:185], v[12:15]
	v_mfma_f32_16x16x32_bf16 v[16:19], v[170:173], v[186:189], v[16:19]
	v_mfma_f32_16x16x32_bf16 v[20:23], v[170:173], v[190:193], v[20:23]
	v_mfma_f32_16x16x32_bf16 v[24:27], v[174:177], v[178:181], v[24:27]
	v_mfma_f32_16x16x32_bf16 v[130:133], v[174:177], v[182:185], v[130:133]
	v_mfma_f32_16x16x32_bf16 v[134:137], v[174:177], v[186:189], v[134:137]
	v_mfma_f32_16x16x32_bf16 v[194:197], v[174:177], v[190:193], v[194:197]
	s_waitcnt vmcnt(0)
; #define LAS __attribute__((address_space(3)))
; #define MFMA16(a, b, c) __builtin_amdgcn_mfma_f32_16x16x32_bf16((a), (b), (c), 0, 0, 0)
; __device__ __forceinline__ void sample_out_block(LAS unsigned char* lds, const bf16_t* A, const bf16_t* Bt, int K, bf16_t* xb, float* sspart, int blk, int tid) {
;     ...
;                     for (int nt = 0; nt < 4; ++nt) acc[ra][nt] = MFMA16(af[s][ra], bf[s][nt], acc[ra][nt]);
; #pragma unroll
;             for (int s = 0; s < 2; ++s) {
; #pragma unroll
;                 for (int ra = 0; ra < 2; ++ra) af[s][ra] = afn[s][ra];
; #pragma unroll
;                 for (int nt = 0; nt < 4; ++nt) bf[s][nt] = bfn[s][nt];
;             }
;         }
;     }
;     LAS f32x4* part = (LAS f32x4*)lds;
; #pragma unroll
;     for (int ra = 0; ra < 2; ++ra)
; #pragma unroll
;         for (int nt = 0; nt < 4; ++nt) part[(wave * 8 + ra * 4 + nt) * 64 + lane] = acc[ra][nt];
;     __syncthreads();
;     if (wave < 2) {
;         const int ra = wave;
;         f32x4 sum[4];
; #pragma unroll
;         for (int nt = 0; nt < 4; ++nt) {
;             sum[nt] = part[(0 * 8 + ra * 4 + nt) * 64 + lane];
; #pragma unroll
;             for (int w = 1; w < 8; ++w) sum[nt] += part[(w * 8 + ra * 4 + nt) * 64 + lane];
	ds_write_b128 v206, v[82:85]
	ds_write_b128 v206, v[86:89] offset:1152
	ds_write_b128 v206, v[90:93] offset:2304
	ds_write_b128 v206, v[94:97] offset:3456
	ds_write_b128 v206, v[98:101] offset:4608
	ds_write_b128 v206, v[102:105] offset:5760
	ds_write_b128 v206, v[106:109] offset:6912
	ds_write_b128 v207, v[110:113]
	ds_write_b128 v207, v[114:117] offset:1152
	ds_write_b128 v207, v[118:121] offset:2304
	ds_write_b128 v207, v[122:125] offset:3456
	ds_write_b128 v207, v[126:129] offset:4608
	ds_read_b128 v[146:149], v208 offset:0
	ds_read_b128 v[150:153], v208 offset:2304
	ds_read_b128 v[154:157], v208 offset:4608
	ds_read_b128 v[158:161], v226
	ds_read_b128 v[162:165], v209 offset:1152
	ds_read_b128 v[166:169], v209 offset:3456
	ds_read_b128 v[170:173], v208 offset:64
	ds_read_b128 v[174:177], v208 offset:2368
	ds_read_b128 v[178:181], v208 offset:4672
	ds_read_b128 v[182:185], v226 offset:64
	ds_read_b128 v[186:189], v209 offset:1216
	ds_read_b128 v[190:193], v209 offset:3520
	s_waitcnt lgkmcnt(6)
	v_mfma_f32_16x16x32_bf16 v[8:11], v[146:149], v[154:157], v[8:11]
	v_mfma_f32_16x16x32_bf16 v[12:15], v[146:149], v[158:161], v[12:15]
	v_mfma_f32_16x16x32_bf16 v[16:19], v[146:149], v[162:165], v[16:19]
	v_mfma_f32_16x16x32_bf16 v[20:23], v[146:149], v[166:169], v[20:23]
	v_mfma_f32_16x16x32_bf16 v[24:27], v[150:153], v[154:157], v[24:27]
	v_mfma_f32_16x16x32_bf16 v[130:133], v[150:153], v[158:161], v[130:133]
	v_mfma_f32_16x16x32_bf16 v[134:137], v[150:153], v[162:165], v[134:137]
	v_mfma_f32_16x16x32_bf16 v[194:197], v[150:153], v[166:169], v[194:197]
	s_waitcnt lgkmcnt(0)
	v_mfma_f32_16x16x32_bf16 v[8:11], v[170:173], v[178:181], v[8:11]
	v_mfma_f32_16x16x32_bf16 v[12:15], v[170:173], v[182:185], v[12:15]
	v_mfma_f32_16x16x32_bf16 v[16:19], v[170:173], v[186:189], v[16:19]
	v_mfma_f32_16x16x32_bf16 v[20:23], v[170:173], v[190:193], v[20:23]
	v_mfma_f32_16x16x32_bf16 v[24:27], v[174:177], v[178:181], v[24:27]
	v_mfma_f32_16x16x32_bf16 v[130:133], v[174:177], v[182:185], v[130:133]
	v_mfma_f32_16x16x32_bf16 v[134:137], v[174:177], v[186:189], v[134:137]
	v_mfma_f32_16x16x32_bf16 v[194:197], v[174:177], v[190:193], v[194:197]
	s_nop 7
	s_nop 7
	ds_write_b128 v32, v[8:11]
	ds_write_b128 v32, v[12:15] offset:1024
	ds_write_b128 v32, v[16:19] offset:2048
	ds_write_b128 v32, v[20:23] offset:3072
	ds_write_b128 v32, v[24:27] offset:4096
	ds_write_b128 v32, v[130:133] offset:5120
	ds_write_b128 v32, v[134:137] offset:6144
	ds_write_b128 v32, v[194:197] offset:7168
	s_waitcnt lgkmcnt(0)
	s_barrier
	s_and_saveexec_b64 s[8:9], s[4:5]
	s_cbranch_execz .LBB0_1164
	ds_read_b128 v[8:11], v33
	ds_read_b128 v[12:15], v33 offset:8192
	s_lshl_b32 s80, s27, 1
	v_lshl_add_u64 v[28:29], v[6:7], 0, s[80:81]
	s_lshl_b32 s10, s20, 2
	s_add_u32 s10, s16, s10
	s_waitcnt lgkmcnt(0)
	v_pk_add_f32 v[14:15], v[10:11], v[14:15]
	v_pk_add_f32 v[12:13], v[8:9], v[12:13]
	ds_read_b128 v[8:11], v33 offset:16384
	s_addc_u32 s11, s17, 0
	s_waitcnt lgkmcnt(0)
	v_pk_add_f32 v[14:15], v[14:15], v[10:11]
	v_pk_add_f32 v[12:13], v[12:13], v[8:9]
	ds_read_b128 v[8:11], v33 offset:24576
	s_waitcnt lgkmcnt(0)
	v_pk_add_f32 v[14:15], v[14:15], v[10:11]
	v_pk_add_f32 v[12:13], v[12:13], v[8:9]
	ds_read_b128 v[8:11], v33 offset:32768
	s_waitcnt lgkmcnt(0)
	v_pk_add_f32 v[14:15], v[14:15], v[10:11]
	v_pk_add_f32 v[12:13], v[12:13], v[8:9]
	ds_read_b128 v[8:11], v33 offset:40960
	s_waitcnt lgkmcnt(0)
	v_pk_add_f32 v[14:15], v[14:15], v[10:11]
	v_pk_add_f32 v[12:13], v[12:13], v[8:9]
	ds_read_b128 v[8:11], v33 offset:49152
	s_waitcnt lgkmcnt(0)
	v_pk_add_f32 v[14:15], v[14:15], v[10:11]
	v_pk_add_f32 v[16:17], v[12:13], v[8:9]
	ds_read_b128 v[8:11], v33 offset:57344
	s_waitcnt lgkmcnt(0)
	v_pk_add_f32 v[12:13], v[14:15], v[10:11]
	v_pk_add_f32 v[20:21], v[16:17], v[8:9]
	ds_read_b128 v[8:11], v33 offset:1024
	ds_read_b128 v[14:17], v33 offset:9216
	s_waitcnt lgkmcnt(0)
	v_pk_add_f32 v[16:17], v[10:11], v[16:17]
	v_pk_add_f32 v[14:15], v[8:9], v[14:15]
	ds_read_b128 v[8:11], v33 offset:17408
	s_waitcnt lgkmcnt(0)
	v_pk_add_f32 v[16:17], v[16:17], v[10:11]
	v_pk_add_f32 v[14:15], v[14:15], v[8:9]
	ds_read_b128 v[8:11], v33 offset:25600
	s_waitcnt lgkmcnt(0)
	v_pk_add_f32 v[16:17], v[16:17], v[10:11]
	v_pk_add_f32 v[14:15], v[14:15], v[8:9]
	ds_read_b128 v[8:11], v33 offset:33792
	s_waitcnt lgkmcnt(0)
	v_pk_add_f32 v[16:17], v[16:17], v[10:11]
	v_pk_add_f32 v[14:15], v[14:15], v[8:9]
	ds_read_b128 v[8:11], v33 offset:41984
	s_waitcnt lgkmcnt(0)
	v_pk_add_f32 v[16:17], v[16:17], v[10:11]
	v_pk_add_f32 v[14:15], v[14:15], v[8:9]
	ds_read_b128 v[8:11], v33 offset:50176
	s_waitcnt lgkmcnt(0)
	v_pk_add_f32 v[16:17], v[16:17], v[10:11]
	v_pk_add_f32 v[14:15], v[14:15], v[8:9]
	ds_read_b128 v[8:11], v33 offset:58368
	s_waitcnt lgkmcnt(0)
	v_pk_add_f32 v[18:19], v[16:17], v[10:11]
	v_pk_add_f32 v[26:27], v[14:15], v[8:9]
	ds_read_b128 v[8:11], v33 offset:2048
	ds_read_b128 v[14:17], v33 offset:10240
	s_waitcnt lgkmcnt(0)
	v_pk_add_f32 v[16:17], v[10:11], v[16:17]
	v_pk_add_f32 v[14:15], v[8:9], v[14:15]
	ds_read_b128 v[8:11], v33 offset:18432
	s_waitcnt lgkmcnt(0)
	v_pk_add_f32 v[16:17], v[16:17], v[10:11]
	v_pk_add_f32 v[14:15], v[14:15], v[8:9]
	ds_read_b128 v[8:11], v33 offset:26624
	s_waitcnt lgkmcnt(0)
	v_pk_add_f32 v[16:17], v[16:17], v[10:11]
	v_pk_add_f32 v[14:15], v[14:15], v[8:9]
	ds_read_b128 v[8:11], v33 offset:34816
	s_waitcnt lgkmcnt(0)
	v_pk_add_f32 v[16:17], v[16:17], v[10:11]
	v_pk_add_f32 v[14:15], v[14:15], v[8:9]
	ds_read_b128 v[8:11], v33 offset:43008
	s_waitcnt lgkmcnt(0)
	v_pk_add_f32 v[16:17], v[16:17], v[10:11]
	v_pk_add_f32 v[14:15], v[14:15], v[8:9]
	ds_read_b128 v[8:11], v33 offset:51200
	s_waitcnt lgkmcnt(0)
; __device__ __forceinline__ float bf1(bf16_t h) { return __uint_as_float((unsigned)h << 16); }
; __device__ __forceinline__ bf16_t f2bf(float f) { return (bf16_t)(pk2(f, 0.f) & 0xffffu); }
; __device__ __forceinline__ void sample_out_block(LAS unsigned char* lds, const bf16_t* A, const bf16_t* Bt, int K, bf16_t* xb, float* sspart, int blk, int tid) {
;     ...
;             for (int w = 1; w < 8; ++w) sum[nt] += part[(w * 8 + ra * 4 + nt) * 64 + lane];
;         }
;         float ss[4] = {0.f, 0.f, 0.f, 0.f};
; #pragma unroll
;         for (int j = 0; j < 4; ++j)
; #pragma unroll
;             for (int nt = 0; nt < 4; ++nt) {
;                 bf16_t* xp = xb + (size_t)(r0 + 16 * ra + 4 * g + j) * 2048 + 64 * cg + 16 * nt + l15;
;                 const bf16_t nv = f2bf(bf1(*xp) + sum[nt][j]);
;                 *xp = nv; const float r = bf1(nv); ss[j] += r * r;
;             }
; #pragma unroll
;         for (int j = 0; j < 4; ++j) {
;             float s = ss[j];
;             s += __shfl_xor(s, 1); s += __shfl_xor(s, 2); s += __shfl_xor(s, 4); s += __shfl_xor(s, 8);
;             if (l15 == 0) sspart[(size_t)(r0 + 16 * ra + 4 * g + j) * 32 + cg] = s;
	v_pk_add_f32 v[16:17], v[16:17], v[10:11]
	v_pk_add_f32 v[14:15], v[14:15], v[8:9]
	ds_read_b128 v[8:11], v33 offset:59392
	s_waitcnt lgkmcnt(0)
	v_pk_add_f32 v[16:17], v[16:17], v[10:11]
	v_pk_add_f32 v[24:25], v[14:15], v[8:9]
	ds_read_b128 v[8:11], v33 offset:3072
	ds_read_b128 v[34:37], v33 offset:11264
	s_waitcnt lgkmcnt(0)
	v_pk_add_f32 v[14:15], v[10:11], v[36:37]
	v_pk_add_f32 v[22:23], v[8:9], v[34:35]
	ds_read_b128 v[8:11], v33 offset:19456
	ds_read_b128 v[34:37], v33 offset:60416
	s_waitcnt lgkmcnt(1)
	v_pk_add_f32 v[14:15], v[14:15], v[10:11]
	v_pk_add_f32 v[22:23], v[22:23], v[8:9]
	ds_read_b128 v[8:11], v33 offset:27648
	s_waitcnt lgkmcnt(0)
	v_pk_add_f32 v[14:15], v[14:15], v[10:11]
	v_pk_add_f32 v[22:23], v[22:23], v[8:9]
	ds_read_b128 v[8:11], v33 offset:35840
	s_waitcnt lgkmcnt(0)
	v_pk_add_f32 v[14:15], v[14:15], v[10:11]
	v_pk_add_f32 v[22:23], v[22:23], v[8:9]
	ds_read_b128 v[8:11], v33 offset:44032
	s_waitcnt lgkmcnt(0)
	v_pk_add_f32 v[14:15], v[14:15], v[10:11]
	v_pk_add_f32 v[22:23], v[22:23], v[8:9]
	ds_read_b128 v[8:11], v33 offset:52224
	s_waitcnt lgkmcnt(0)
	v_pk_add_f32 v[10:11], v[14:15], v[10:11]
	v_pk_add_f32 v[14:15], v[22:23], v[8:9]
	v_pk_add_f32 v[8:9], v[10:11], v[36:37]
	v_add_u32_e32 v10, s21, v31
	v_ashrrev_i32_e32 v11, 31, v10
	v_pk_add_f32 v[22:23], v[14:15], v[34:35]
	v_lshlrev_b64 v[14:15], 12, v[10:11]
	v_lshl_add_u64 v[14:15], v[28:29], 0, v[14:15]
	global_load_ushort v0, v[14:15], off
	s_waitcnt vmcnt(0)
	v_lshlrev_b32_e32 v0, 16, v0
	v_add_f32_e32 v0, v20, v0
	v_cvt_pk_bf16_f32 v0, v0, s0
	global_store_short v[14:15], v0, off
	v_lshlrev_b32_e32 v20, 16, v0
	global_load_ushort v0, v[14:15], off offset:32
	s_waitcnt vmcnt(0)
	v_lshlrev_b32_e32 v0, 16, v0
	v_add_f32_e32 v0, v26, v0
	v_cvt_pk_bf16_f32 v0, v0, s0
	global_store_short v[14:15], v0, off offset:32
	v_lshlrev_b32_e32 v0, 16, v0
	v_mul_f32_e32 v0, v0, v0
	v_fmac_f32_e32 v0, v20, v20
	global_load_ushort v20, v[14:15], off offset:64
	s_waitcnt vmcnt(0)
	v_lshlrev_b32_e32 v20, 16, v20
	v_add_f32_e32 v20, v24, v20
	v_cvt_pk_bf16_f32 v20, v20, s0
	global_store_short v[14:15], v20, off offset:64
	v_lshlrev_b32_e32 v20, 16, v20
	v_fmac_f32_e32 v0, v20, v20
	global_load_ushort v20, v[14:15], off offset:96
	s_waitcnt vmcnt(0)
	v_lshlrev_b32_e32 v20, 16, v20
	v_add_f32_e32 v20, v22, v20
	v_cvt_pk_bf16_f32 v20, v20, s0
	global_store_short v[14:15], v20, off offset:96
	v_lshlrev_b32_e32 v14, 16, v20
	v_fmac_f32_e32 v0, v14, v14
	v_or_b32_e32 v14, 1, v10
	v_ashrrev_i32_e32 v15, 31, v14
	v_lshlrev_b64 v[34:35], 12, v[14:15]
	v_lshl_add_u64 v[36:37], v[28:29], 0, v[34:35]
	global_load_ushort v20, v[36:37], off
	s_waitcnt vmcnt(0)
	v_lshlrev_b32_e32 v20, 16, v20
	v_add_f32_e32 v20, v21, v20
	v_cvt_pk_bf16_f32 v26, v20, s0
	global_load_ushort v20, v[36:37], off offset:32
	s_waitcnt vmcnt(0)
	v_lshlrev_b32_e32 v20, 16, v20
	v_add_f32_e32 v20, v27, v20
	v_cvt_pk_bf16_f32 v27, v20, s0
	global_load_ushort v20, v[36:37], off offset:64
	s_waitcnt vmcnt(0)
	v_lshlrev_b32_e32 v20, 16, v20
	v_add_f32_e32 v20, v25, v20
	v_cvt_pk_bf16_f32 v34, v20, s0
	global_load_ushort v20, v[36:37], off offset:96
	s_waitcnt vmcnt(0)
	v_lshlrev_b32_e32 v20, 16, v20
	v_add_f32_e32 v20, v23, v20
	v_cvt_pk_bf16_f32 v35, v20, s0
	v_or_b32_e32 v20, 2, v10
	v_ashrrev_i32_e32 v21, 31, v20
	v_lshlrev_b64 v[22:23], 12, v[20:21]
	v_lshl_add_u64 v[22:23], v[28:29], 0, v[22:23]
	global_load_ushort v24, v[22:23], off
	s_waitcnt vmcnt(0)
	v_lshlrev_b32_e32 v24, 16, v24
	v_add_f32_e32 v12, v12, v24
	global_load_ushort v24, v[22:23], off offset:32
	v_cvt_pk_bf16_f32 v12, v12, s0
	global_store_short v[22:23], v12, off
	global_store_short v[36:37], v26, off
	global_store_short v[36:37], v27, off offset:32
	global_store_short v[36:37], v34, off offset:64
	global_store_short v[36:37], v35, off offset:96
	v_xor_b32_e32 v36, 8, v215
	s_waitcnt vmcnt(5)
	v_lshlrev_b32_e32 v24, 16, v24
	v_add_f32_e32 v18, v18, v24
	global_load_ushort v24, v[22:23], off offset:64
	v_cvt_pk_bf16_f32 v18, v18, s0
	global_store_short v[22:23], v18, off offset:32
	s_waitcnt vmcnt(1)
	v_lshlrev_b32_e32 v24, 16, v24
	v_add_f32_e32 v16, v16, v24
	global_load_ushort v24, v[22:23], off offset:96
	v_cvt_pk_bf16_f32 v16, v16, s0
	global_store_short v[22:23], v16, off offset:64
	s_waitcnt vmcnt(1)
	v_lshlrev_b32_e32 v24, 16, v24
	v_add_f32_e32 v8, v8, v24
	v_cvt_pk_bf16_f32 v8, v8, s0
	global_store_short v[22:23], v8, off offset:96
	v_or_b32_e32 v22, 3, v10
	v_ashrrev_i32_e32 v23, 31, v22
	v_lshlrev_b64 v[24:25], 12, v[22:23]
	v_lshl_add_u64 v[24:25], v[28:29], 0, v[24:25]
	global_load_ushort v28, v[24:25], off
	s_waitcnt vmcnt(0)
	v_lshlrev_b32_e32 v28, 16, v28
	v_add_f32_e32 v13, v13, v28
	global_load_ushort v28, v[24:25], off offset:32
	v_cvt_pk_bf16_f32 v13, v13, s0
	global_store_short v[24:25], v13, off
	s_waitcnt vmcnt(1)
	v_lshlrev_b32_e32 v28, 16, v28
	v_add_f32_e32 v19, v19, v28
	global_load_ushort v28, v[24:25], off offset:64
	v_cvt_pk_bf16_f32 v19, v19, s0
	global_store_short v[24:25], v19, off offset:32
	s_waitcnt vmcnt(1)
	v_lshlrev_b32_e32 v28, 16, v28
	v_add_f32_e32 v17, v17, v28
	global_load_ushort v28, v[24:25], off offset:96
	v_cvt_pk_bf16_f32 v17, v17, s0
	global_store_short v[24:25], v17, off offset:64
	s_waitcnt vmcnt(1)
	v_lshlrev_b32_e32 v28, 16, v28
	v_add_f32_e32 v9, v9, v28
	v_cvt_pk_bf16_f32 v9, v9, s0
	global_store_short v[24:25], v9, off offset:96
	v_and_b32_e32 v25, 64, v215
	v_xor_b32_e32 v24, 1, v215
	v_add_u32_e32 v29, 64, v25
	v_cmp_lt_i32_e32 vcc, v24, v29
	v_xor_b32_e32 v25, 2, v215
	v_xor_b32_e32 v28, 4, v215
	v_cndmask_b32_e32 v24, v215, v24, vcc
	v_cmp_lt_i32_e32 vcc, v25, v29
	v_lshlrev_b32_e32 v24, 2, v24
	s_nop 0
	v_cndmask_b32_e32 v25, v215, v25, vcc
	v_cmp_lt_i32_e32 vcc, v28, v29
	v_lshlrev_b32_e32 v25, 2, v25
	s_nop 0
	v_cndmask_b32_e32 v28, v215, v28, vcc
	v_cmp_lt_i32_e32 vcc, v36, v29
	v_lshlrev_b32_e32 v28, 2, v28
	s_nop 0
	v_cndmask_b32_e32 v29, v215, v36, vcc
	ds_bpermute_b32 v36, v24, v0
	v_lshlrev_b32_e32 v29, 2, v29
	s_waitcnt lgkmcnt(0)
	v_add_f32_e32 v0, v0, v36
	ds_bpermute_b32 v36, v25, v0
	s_waitcnt lgkmcnt(0)
	v_add_f32_e32 v0, v0, v36
	ds_bpermute_b32 v36, v28, v0
	s_waitcnt lgkmcnt(0)
	v_add_f32_e32 v0, v0, v36
	ds_bpermute_b32 v36, v29, v0
	s_and_saveexec_b64 s[20:21], s[6:7]
	s_cbranch_execz .LBB0_1168
	v_lshlrev_b64 v[10:11], 7, v[10:11]
	v_lshl_add_u64 v[10:11], s[10:11], 0, v[10:11]
	s_waitcnt lgkmcnt(0)
	v_add_f32_e32 v0, v0, v36
	global_store_dword v[10:11], v0, off

; #define LAS __attribute__((address_space(3)))
; __device__ __forceinline__ void p0_transpose_item(const float* W, int K, int N, bf16_t* WT, int row_off, LAS float* scr, int item, int lane,
;                                                   const float* gain, int sc_lo, int sc_hi, float sc) {
;     const int nblk = N / 32, kb = item / nblk, nb = item % nblk, k0 = 64 * kb, n0 = 32 * nb;
;     f32x4 wv[8];
; #pragma unroll
;     for (int i = 0; i < 8; ++i) wv[i] = *(const f32x4*)(W + (size_t)(k0 + (lane >> 3) + 8 * i) * N + n0 + 4 * (lane & 7));
; #pragma unroll
;     for (int i = 0; i < 8; ++i) {
;         const int kk = (lane >> 3) + 8 * i;
;         const float gm = gain ? gain[k0 + kk] : 1.0f;
;         LAS float* sp = scr + kk * 33 + 4 * (lane & 7);
;         sp[0] = wv[i][0] * gm; sp[1] = wv[i][1] * gm; sp[2] = wv[i][2] * gm; sp[3] = wv[i][3] * gm;
;     }
.Lp0x_start:
	s_cmpk_lg_i32 s88, 0x100
	s_cbranch_scc1 .LBB0_1317
	s_cmpk_lt_i32 s90, 132
	s_cbranch_scc1 .LBB0_1317
	v_readlane_b32 s4, v254, 38
	v_readfirstlane_b32 s5, v139
	s_lshr_b32 s5, s5, 6
	s_cmp_gt_u32 s4, 1
	s_cbranch_scc1 .LBB0_1317
	s_sub_i32 s43, s90, 132
	s_lshl_b32 s43, s43, 3
	s_add_i32 s43, s43, s5
	s_movk_i32 s7, 0x3e0
	v_lshrrev_b32_e32 v2, 3, v215
	v_and_b32_e32 v3, 7, v215
	v_lshlrev_b32_e32 v5, 2, v2
	s_lshl_b32 s8, s5, 14
	v_mul_u32_u24_e32 v6, 0x84, v2
	v_lshl_add_u32 v6, v3, 4, v6
	v_add_u32_e32 v6, s8, v6
	v_mul_u32_u24_e32 v7, 0x420, v3
	v_lshl_add_u32 v7, v2, 2, v7
	v_add_u32_e32 v7, s8, v7
	s_cmp_eq_u32 s4, 1
	s_cbranch_scc1 .Lp0x_l1
	s_load_dwordx2 s[26:27], s[96:97], 0x80
	s_load_dwordx2 s[28:29], s[96:97], 0x40
	v_readlane_b32 s30, v254, 42
	v_readlane_b32 s31, v254, 43
	v_mul_u32_u24_e32 v4, 0xc000, v2
	v_lshl_add_u32 v4, v3, 4, v4
	v_mul_u32_u24_e32 v8, 0x1000, v2
	v_lshl_add_u32 v8, v3, 4, v8
	s_add_i32 s6, s43, 0x0
	s_waitcnt lgkmcnt(0)
	s_add_u32 s26, s26, 0x6000000
	s_addc_u32 s27, s27, 0
	s_add_u32 s28, s28, 0x6000
	s_addc_u32 s29, s29, 0
	s_add_u32 s30, s30, 0x6a00000
	s_addc_u32 s31, s31, 0
	s_cmpk_ge_i32 s6, 0x3000
	s_cbranch_scc1 .Lp0x_done_ir0
	s_lshr_b32 s9, s6, 7
	s_mul_i32 s9, s9, 0xaaab
	s_lshr_b32 s9, s9, 17
	s_mul_i32 s12, s9, 0x180
	s_sub_i32 s12, s6, s12
	s_mul_i32 s13, s9, 0x300000
	s_lshl_b32 s34, s12, 7
	s_add_i32 s13, s13, s34
	s_add_u32 s36, s26, s13
	s_addc_u32 s37, s27, 0
	global_load_dwordx4 v[10:13], v4, s[36:37]
	s_add_u32 s36, s36, 0x60000
	s_addc_u32 s37, s37, 0
	global_load_dwordx4 v[14:17], v4, s[36:37]
	s_add_u32 s36, s36, 0x60000
	s_addc_u32 s37, s37, 0
	global_load_dwordx4 v[18:21], v4, s[36:37]
	s_add_u32 s36, s36, 0x60000
	s_addc_u32 s37, s37, 0
	global_load_dwordx4 v[22:25], v4, s[36:37]
	s_add_u32 s36, s36, 0x60000
	s_addc_u32 s37, s37, 0
	global_load_dwordx4 v[26:29], v4, s[36:37]
	s_add_u32 s36, s36, 0x60000
	s_addc_u32 s37, s37, 0
	global_load_dwordx4 v[30:33], v4, s[36:37]
	s_add_u32 s36, s36, 0x60000
	s_addc_u32 s37, s37, 0
	global_load_dwordx4 v[34:37], v4, s[36:37]
	s_add_u32 s36, s36, 0x60000
	s_addc_u32 s37, s37, 0
	global_load_dwordx4 v[38:41], v4, s[36:37]
	s_lshl_b32 s34, s9, 8
	s_add_u32 s38, s28, s34
	s_addc_u32 s39, s29, 0
	global_load_dword v42, v5, s[38:39]
	global_load_dword v43, v5, s[38:39] offset:32
	global_load_dword v44, v5, s[38:39] offset:64
	global_load_dword v45, v5, s[38:39] offset:96
	global_load_dword v46, v5, s[38:39] offset:128
	global_load_dword v47, v5, s[38:39] offset:160
	global_load_dword v48, v5, s[38:39] offset:192
	global_load_dword v49, v5, s[38:39] offset:224

; #define LAS __attribute__((address_space(3)))
; #define SEG(cnt, ...) if (r < (cnt)) { p0_transpose_item(__VA_ARGS__); continue; } r -= (cnt);
; __device__ __forceinline__ void p0_transpose_item(const float* W, int K, int N, bf16_t* WT, int row_off, LAS float* scr, int item, int lane,
;                                                   const float* gain, int sc_lo, int sc_hi, float sc) {
;     const int nblk = N / 32, kb = item / nblk, nb = item % nblk, k0 = 64 * kb, n0 = 32 * nb;
;     f32x4 wv[8];
; #pragma unroll
;     for (int i = 0; i < 8; ++i) wv[i] = *(const f32x4*)(W + (size_t)(k0 + (lane >> 3) + 8 * i) * N + n0 + 4 * (lane & 7));
; #pragma unroll
;     for (int i = 0; i < 8; ++i) {
;         const int kk = (lane >> 3) + 8 * i;
;         const float gm = gain ? gain[k0 + kk] : 1.0f;
;         LAS float* sp = scr + kk * 33 + 4 * (lane & 7);
;         sp[0] = wv[i][0] * gm; sp[1] = wv[i][1] * gm; sp[2] = wv[i][2] * gm; sp[3] = wv[i][3] * gm;
;     }
; __global__ void __launch_bounds__(NTHREADS, 2) hybrid_fwd(Params P) {
;     ...
;             SEG(5376, w_in_even + (size_t)2048 * EIN, 2048, EIN, WinE + (size_t)EIN * 2048, 0, scr, r, lane, norm_mix + 2 * 2048, 0, 0, 1.f)
.Lp0x_l1:
	s_load_dwordx2 s[26:27], s[96:97], 0x48
	s_load_dwordx2 s[28:29], s[96:97], 0x40
	v_readlane_b32 s30, v254, 42
	v_readlane_b32 s31, v254, 43
	v_mul_u32_u24_e32 v4, 0x5400, v2
	v_lshl_add_u32 v4, v3, 4, v4
	v_mul_u32_u24_e32 v8, 0x1000, v2
	v_lshl_add_u32 v8, v3, 4, v8
	s_add_i32 s6, s43, 0x0
	s_waitcnt lgkmcnt(0)
	s_add_u32 s26, s26, 0x2a00000
	s_addc_u32 s27, s27, 0
	s_add_u32 s28, s28, 0x4000
	s_addc_u32 s29, s29, 0
	s_add_u32 s30, s30, 0x1500000
	s_addc_u32 s31, s31, 0
	s_cmpk_ge_i32 s6, 0x1500
	s_cbranch_scc1 .Lp0x_done_ie
	s_lshr_b32 s9, s6, 3
	s_mul_i32 s9, s9, 0xc31
	s_lshr_b32 s9, s9, 16
	s_mul_i32 s12, s9, 0xa8
	s_sub_i32 s12, s6, s12
	s_mul_i32 s13, s9, 0x150000
	s_lshl_b32 s34, s12, 7
	s_add_i32 s13, s13, s34
	s_add_u32 s36, s26, s13
	s_addc_u32 s37, s27, 0
	global_load_dwordx4 v[10:13], v4, s[36:37]
	s_add_u32 s36, s36, 0x2a000
	s_addc_u32 s37, s37, 0
	global_load_dwordx4 v[14:17], v4, s[36:37]
	s_add_u32 s36, s36, 0x2a000
	s_addc_u32 s37, s37, 0
	global_load_dwordx4 v[18:21], v4, s[36:37]
	s_add_u32 s36, s36, 0x2a000
	s_addc_u32 s37, s37, 0
	global_load_dwordx4 v[22:25], v4, s[36:37]
	s_add_u32 s36, s36, 0x2a000
	s_addc_u32 s37, s37, 0
	global_load_dwordx4 v[26:29], v4, s[36:37]
	s_add_u32 s36, s36, 0x2a000
	s_addc_u32 s37, s37, 0
	global_load_dwordx4 v[30:33], v4, s[36:37]
	s_add_u32 s36, s36, 0x2a000
	s_addc_u32 s37, s37, 0
	global_load_dwordx4 v[34:37], v4, s[36:37]
	s_add_u32 s36, s36, 0x2a000
	s_addc_u32 s37, s37, 0
	global_load_dwordx4 v[38:41], v4, s[36:37]
	s_lshl_b32 s34, s9, 8
	s_add_u32 s38, s28, s34
	s_addc_u32 s39, s29, 0
	global_load_dword v42, v5, s[38:39]
	global_load_dword v43, v5, s[38:39] offset:32
	global_load_dword v44, v5, s[38:39] offset:64
	global_load_dword v45, v5, s[38:39] offset:96
	global_load_dword v46, v5, s[38:39] offset:128
	global_load_dword v47, v5, s[38:39] offset:160
	global_load_dword v48, v5, s[38:39] offset:192
	global_load_dword v49, v5, s[38:39] offset:224

; #define SEG(cnt, ...) if (r < (cnt)) { p0_transpose_item(__VA_ARGS__); continue; } r -= (cnt);
; __device__ __forceinline__ void p0_transpose_item(const float* W, int K, int N, bf16_t* WT, int row_off, LAS float* scr, int item, int lane,
;                                                   const float* gain, int sc_lo, int sc_hi, float sc) {
;     const int nblk = N / 32, kb = item / nblk, nb = item % nblk, k0 = 64 * kb, n0 = 32 * nb;
;     f32x4 wv[8];
; #pragma unroll
;     for (int i = 0; i < 8; ++i) wv[i] = *(const f32x4*)(W + (size_t)(k0 + (lane >> 3) + 8 * i) * N + n0 + 4 * (lane & 7));
; __global__ void __launch_bounds__(NTHREADS, 2) hybrid_fwd(Params P) {
;     ...
;             SEG(4096, w_out_ret + (size_t)4096 * 2048, 4096, 2048, WoutR + (size_t)2048 * 4096, 0, scr, r, lane, nullptr, 0, 0, 1.f)
.Lp0x_done_ie:
	s_load_dwordx2 s[26:27], s[96:97], 0x88
	v_readlane_b32 s30, v254, 42
	v_readlane_b32 s31, v254, 43
	v_mul_u32_u24_e32 v4, 0x2000, v2
	v_lshl_add_u32 v4, v3, 4, v4
	v_mul_u32_u24_e32 v8, 0x2000, v2
	v_lshl_add_u32 v8, v3, 4, v8
	s_add_i32 s6, s43, 0x0
	s_waitcnt lgkmcnt(0)
	s_add_u32 s26, s26, 0x2000000
	s_addc_u32 s27, s27, 0
	s_add_u32 s30, s30, 0xaa00000
	s_addc_u32 s31, s31, 0
	s_cmpk_ge_i32 s6, 0x1000
	s_cbranch_scc1 .Lp0x_done_or
	s_lshr_b32 s9, s6, 6
	s_and_b32 s12, s6, 63
	s_mul_i32 s13, s9, 0x80000
	s_lshl_b32 s34, s12, 7
	s_add_i32 s13, s13, s34
	s_add_u32 s36, s26, s13
	s_addc_u32 s37, s27, 0
	global_load_dwordx4 v[10:13], v4, s[36:37]
	s_add_u32 s36, s36, 0x10000
	s_addc_u32 s37, s37, 0
	global_load_dwordx4 v[14:17], v4, s[36:37]
	s_add_u32 s36, s36, 0x10000
	s_addc_u32 s37, s37, 0
	global_load_dwordx4 v[18:21], v4, s[36:37]
	s_add_u32 s36, s36, 0x10000
	s_addc_u32 s37, s37, 0
	global_load_dwordx4 v[22:25], v4, s[36:37]
	s_add_u32 s36, s36, 0x10000
	s_addc_u32 s37, s37, 0
	global_load_dwordx4 v[26:29], v4, s[36:37]
	s_add_u32 s36, s36, 0x10000
	s_addc_u32 s37, s37, 0
	global_load_dwordx4 v[30:33], v4, s[36:37]
	s_add_u32 s36, s36, 0x10000
	s_addc_u32 s37, s37, 0
	global_load_dwordx4 v[34:37], v4, s[36:37]
	s_add_u32 s36, s36, 0x10000
	s_addc_u32 s37, s37, 0
	global_load_dwordx4 v[38:41], v4, s[36:37]

; #define SEG(cnt, ...) if (r < (cnt)) { p0_transpose_item(__VA_ARGS__); continue; } r -= (cnt);
; __device__ __forceinline__ void p0_transpose_item(const float* W, int K, int N, bf16_t* WT, int row_off, LAS float* scr, int item, int lane,
;                                                   const float* gain, int sc_lo, int sc_hi, float sc) {
;     const int nblk = N / 32, kb = item / nblk, nb = item % nblk, k0 = 64 * kb, n0 = 32 * nb;
;     f32x4 wv[8];
; #pragma unroll
;     for (int i = 0; i < 8; ++i) wv[i] = *(const f32x4*)(W + (size_t)(k0 + (lane >> 3) + 8 * i) * N + n0 + 4 * (lane & 7));
; __global__ void __launch_bounds__(NTHREADS, 2) hybrid_fwd(Params P) {
;     ...
;             SEG(2048, w_out_even + (size_t)2048 * 2048, 2048, 2048, WoutE + (size_t)2048 * 2048, 0, scr, r, lane, nullptr, 0, 0, 1.f)
.Lp0x_done_or:
	s_load_dwordx2 s[26:27], s[96:97], 0x78
	v_readlane_b32 s30, v254, 42
	v_readlane_b32 s31, v254, 43
	v_mul_u32_u24_e32 v4, 0x2000, v2
	v_lshl_add_u32 v4, v3, 4, v4
	v_mul_u32_u24_e32 v8, 0x1000, v2
	v_lshl_add_u32 v8, v3, 4, v8
	s_add_i32 s6, s43, 0x0
	s_waitcnt lgkmcnt(0)
	s_add_u32 s26, s26, 0x1000000
	s_addc_u32 s27, s27, 0
	s_add_u32 s30, s30, 0x3200000
	s_addc_u32 s31, s31, 0
	s_cmpk_ge_i32 s6, 0x800
	s_cbranch_scc1 .Lp0x_done_oe
	s_lshr_b32 s9, s6, 6
	s_and_b32 s12, s6, 63
	s_mul_i32 s13, s9, 0x80000
	s_lshl_b32 s34, s12, 7
	s_add_i32 s13, s13, s34
	s_add_u32 s36, s26, s13
	s_addc_u32 s37, s27, 0
	global_load_dwordx4 v[10:13], v4, s[36:37]
	s_add_u32 s36, s36, 0x10000
	s_addc_u32 s37, s37, 0
	global_load_dwordx4 v[14:17], v4, s[36:37]
	s_add_u32 s36, s36, 0x10000
	s_addc_u32 s37, s37, 0
	global_load_dwordx4 v[18:21], v4, s[36:37]
	s_add_u32 s36, s36, 0x10000
	s_addc_u32 s37, s37, 0
	global_load_dwordx4 v[22:25], v4, s[36:37]
	s_add_u32 s36, s36, 0x10000
	s_addc_u32 s37, s37, 0
	global_load_dwordx4 v[26:29], v4, s[36:37]
	s_add_u32 s36, s36, 0x10000
	s_addc_u32 s37, s37, 0
	global_load_dwordx4 v[30:33], v4, s[36:37]
	s_add_u32 s36, s36, 0x10000
	s_addc_u32 s37, s37, 0
	global_load_dwordx4 v[34:37], v4, s[36:37]
	s_add_u32 s36, s36, 0x10000
	s_addc_u32 s37, s37, 0
	global_load_dwordx4 v[38:41], v4, s[36:37]
